# adaLN unit v2: mat-vec with even/odd-k packed FMA accumulation (no shuffle moves), 11-deep weight ring with first 6 trips issued before the silu math
# speedup vs baseline: 1.0006x; 1.0006x over previous
.LBB0_34:
	s_or_saveexec_b64 s[0:1], s[52:53]
	s_mov_b64 s[52:53], 0
	s_xor_b64 exec, exec, s[0:1]
	s_cbranch_execz .LBB0_42
	v_mov_b32_e32 v2, v80
	v_mov_b32_e32 v3, v7
	v_mov_b32_e32 v4, s65
	v_mov_b32_e32 v5, s66
	v_mov_b32_e32 v8, s72
	ds_read_b64 v[252:253], v4
	ds_read_b64 v[254:255], v5
	ds_read_b64 v[194:195], v8
	v_lshlrev_b32_e32 v8, 2, v3
	v_lshlrev_b32_e32 v4, 2, v60
	s_waitcnt lgkmcnt(0)
	v_add_co_u32_e32 v252, vcc, v252, v8
	v_addc_co_u32_e32 v253, vcc, 0, v253, vcc
	v_add_co_u32_e32 v254, vcc, v254, v8
	v_addc_co_u32_e32 v255, vcc, 0, v255, vcc
	v_add_co_u32_e32 v194, vcc, v194, v10
	v_addc_co_u32_e32 v195, vcc, v195, v11, vcc
	v_add_co_u32_e32 v194, vcc, v194, v4
	v_addc_co_u32_e32 v195, vcc, 0, v195, vcc
	global_load_dword v214, v[252:253], off
	global_load_dword v215, v[252:253], off offset:1024
	global_load_dword v216, v[252:253], off offset:2048
	global_load_dword v217, v[252:253], off offset:3072
	v_add_co_u32_e32 v252, vcc, 0x1000, v252
	v_addc_co_u32_e32 v253, vcc, 0, v253, vcc
	global_load_dword v218, v[252:253], off
	global_load_dword v219, v[252:253], off offset:1024
	global_load_dword v220, v[252:253], off offset:2048
	global_load_dword v221, v[252:253], off offset:3072
	v_add_co_u32_e32 v252, vcc, 0x1000, v252
	v_addc_co_u32_e32 v253, vcc, 0, v253, vcc
	global_load_dword v222, v[252:253], off
	global_load_dword v223, v[252:253], off offset:1024
	global_load_dword v224, v[252:253], off offset:2048
	global_load_dword v225, v[252:253], off offset:3072
	v_add_co_u32_e32 v252, vcc, 0x1000, v252
	v_addc_co_u32_e32 v253, vcc, 0, v253, vcc
	global_load_dword v226, v[252:253], off
	global_load_dword v227, v[252:253], off offset:1024
	global_load_dword v228, v[252:253], off offset:2048
	global_load_dword v229, v[252:253], off offset:3072
	v_add_co_u32_e32 v252, vcc, 0x1000, v252
	v_addc_co_u32_e32 v253, vcc, 0, v253, vcc
	global_load_dword v230, v[252:253], off
	global_load_dword v231, v[252:253], off offset:1024
	global_load_dword v232, v[252:253], off offset:2048
	global_load_dword v233, v[252:253], off offset:3072
	v_add_co_u32_e32 v252, vcc, 0x1000, v252
	v_addc_co_u32_e32 v253, vcc, 0, v253, vcc
	global_load_dword v234, v[252:253], off
	global_load_dword v235, v[252:253], off offset:1024
	global_load_dword v236, v[252:253], off offset:2048
	global_load_dword v237, v[252:253], off offset:3072
	v_add_co_u32_e32 v252, vcc, 0x1000, v252
	v_addc_co_u32_e32 v253, vcc, 0, v253, vcc
	global_load_dword v239, v[252:253], off
	global_load_dword v240, v[252:253], off offset:1024
	global_load_dword v241, v[252:253], off offset:2048
	global_load_dword v242, v[252:253], off offset:3072
	v_add_co_u32_e32 v252, vcc, 0x1000, v252
	v_addc_co_u32_e32 v253, vcc, 0, v253, vcc
	global_load_dword v243, v[252:253], off
	global_load_dword v244, v[252:253], off offset:1024
	global_load_dword v245, v[252:253], off offset:2048
	global_load_dword v246, v[252:253], off offset:3072
	global_load_dword v247, v[254:255], off
	global_load_dword v248, v[254:255], off offset:1024
	global_load_dword v249, v[254:255], off offset:2048
	global_load_dword v250, v[254:255], off offset:3072
	global_load_dword v150, v[194:195], off
	v_add_co_u32_e32 v194, vcc, 0x6000, v194
	v_addc_co_u32_e32 v195, vcc, 0, v195, vcc
	global_load_dword v151, v[194:195], off
	v_add_co_u32_e32 v194, vcc, 0x6000, v194
	v_addc_co_u32_e32 v195, vcc, 0, v195, vcc
	global_load_dword v152, v[194:195], off
	v_add_co_u32_e32 v194, vcc, 0x6000, v194
	v_addc_co_u32_e32 v195, vcc, 0, v195, vcc
	global_load_dword v153, v[194:195], off
	v_add_co_u32_e32 v194, vcc, 0x6000, v194
	v_addc_co_u32_e32 v195, vcc, 0, v195, vcc
	global_load_dword v154, v[194:195], off
	v_add_co_u32_e32 v194, vcc, 0x6000, v194
	v_addc_co_u32_e32 v195, vcc, 0, v195, vcc
	global_load_dword v155, v[194:195], off
	v_add_co_u32_e32 v194, vcc, 0x6000, v194
	v_addc_co_u32_e32 v195, vcc, 0, v195, vcc
	global_load_dword v156, v[194:195], off
	v_add_co_u32_e32 v194, vcc, 0x6000, v194
	v_addc_co_u32_e32 v195, vcc, 0, v195, vcc
	global_load_dword v157, v[194:195], off
	v_add_co_u32_e32 v194, vcc, 0x6000, v194
	v_addc_co_u32_e32 v195, vcc, 0, v195, vcc
	global_load_dword v158, v[194:195], off
	v_add_co_u32_e32 v194, vcc, 0x6000, v194
	v_addc_co_u32_e32 v195, vcc, 0, v195, vcc
	global_load_dword v159, v[194:195], off
	v_add_co_u32_e32 v194, vcc, 0x6000, v194
	v_addc_co_u32_e32 v195, vcc, 0, v195, vcc
	global_load_dword v160, v[194:195], off
	v_add_co_u32_e32 v194, vcc, 0x6000, v194
	v_addc_co_u32_e32 v195, vcc, 0, v195, vcc
	global_load_dword v161, v[194:195], off
	v_add_co_u32_e32 v194, vcc, 0x6000, v194
	v_addc_co_u32_e32 v195, vcc, 0, v195, vcc
	global_load_dword v162, v[194:195], off
	v_add_co_u32_e32 v194, vcc, 0x6000, v194
	v_addc_co_u32_e32 v195, vcc, 0, v195, vcc
	global_load_dword v163, v[194:195], off
	v_add_co_u32_e32 v194, vcc, 0x6000, v194
	v_addc_co_u32_e32 v195, vcc, 0, v195, vcc
	global_load_dword v164, v[194:195], off
	v_add_co_u32_e32 v194, vcc, 0x6000, v194
	v_addc_co_u32_e32 v195, vcc, 0, v195, vcc
	global_load_dword v165, v[194:195], off
	v_add_co_u32_e32 v194, vcc, 0x6000, v194
	v_addc_co_u32_e32 v195, vcc, 0, v195, vcc
	global_load_dword v166, v[194:195], off
	v_add_co_u32_e32 v194, vcc, 0x6000, v194
	v_addc_co_u32_e32 v195, vcc, 0, v195, vcc
	global_load_dword v167, v[194:195], off
	v_add_co_u32_e32 v194, vcc, 0x6000, v194
	v_addc_co_u32_e32 v195, vcc, 0, v195, vcc
	global_load_dword v168, v[194:195], off
	v_add_co_u32_e32 v194, vcc, 0x6000, v194
	v_addc_co_u32_e32 v195, vcc, 0, v195, vcc
	global_load_dword v169, v[194:195], off
	v_add_co_u32_e32 v194, vcc, 0x6000, v194
	v_addc_co_u32_e32 v195, vcc, 0, v195, vcc
	global_load_dword v170, v[194:195], off
	v_add_co_u32_e32 v194, vcc, 0x6000, v194
	v_addc_co_u32_e32 v195, vcc, 0, v195, vcc
	global_load_dword v171, v[194:195], off
	v_add_co_u32_e32 v194, vcc, 0x6000, v194
	v_addc_co_u32_e32 v195, vcc, 0, v195, vcc
	global_load_dword v172, v[194:195], off
	v_add_co_u32_e32 v194, vcc, 0x6000, v194
	v_addc_co_u32_e32 v195, vcc, 0, v195, vcc
	global_load_dword v173, v[194:195], off
	v_add_co_u32_e32 v194, vcc, 0x6000, v194
	v_addc_co_u32_e32 v195, vcc, 0, v195, vcc
	s_waitcnt vmcnt(59)
	v_mov_b32_e32 v4, v214
	v_mul_f32_e32 v5, 0xbfb8aa3b, v4
	v_fma_f32 v8, v4, s67, -v5
	v_rndne_f32_e32 v23, v5
	v_fmac_f32_e32 v8, 0xb2a5705f, v4
	v_sub_f32_e32 v5, v5, v23
	v_add_f32_e32 v5, v5, v8
	v_cvt_i32_f32_e32 v23, v23
	v_exp_f32_e32 v5, v5
	v_cmp_nlt_f32_e32 vcc, s68, v4
	v_ldexp_f32 v5, v5, v23
	s_nop 0
	v_cndmask_b32_e32 v5, 0, v5, vcc
	v_cmp_ngt_f32_e32 vcc, s69, v4
	s_nop 1
	v_cndmask_b32_e32 v5, v95, v5, vcc
	v_add_f32_e32 v5, 1.0, v5
	v_div_scale_f32 v8, s[54:55], v5, v5, v4
	v_rcp_f32_e32 v23, v8
	v_div_scale_f32 v61, vcc, v4, v5, v4
	v_fma_f32 v65, -v8, v23, 1.0
	v_fmac_f32_e32 v23, v65, v23
	v_mul_f32_e32 v65, v61, v23
	v_fma_f32 v66, -v8, v65, v61
	v_fmac_f32_e32 v65, v66, v23
	v_fma_f32 v8, -v8, v65, v61
	v_div_fmas_f32 v8, v8, v23, v65
	v_div_fixup_f32 v4, v8, v5, v4
	ds_write_b32 v2, v4
	s_waitcnt vmcnt(58)
	v_mov_b32_e32 v4, v215
	v_mul_f32_e32 v5, 0xbfb8aa3b, v4
	v_fma_f32 v8, v4, s67, -v5
	v_rndne_f32_e32 v23, v5
	v_fmac_f32_e32 v8, 0xb2a5705f, v4
	v_sub_f32_e32 v5, v5, v23
	v_add_f32_e32 v5, v5, v8
	v_cvt_i32_f32_e32 v23, v23
	v_exp_f32_e32 v5, v5
	v_cmp_nlt_f32_e32 vcc, s68, v4
	v_ldexp_f32 v5, v5, v23
	s_nop 0
	v_cndmask_b32_e32 v5, 0, v5, vcc
	v_cmp_ngt_f32_e32 vcc, s69, v4
	s_nop 1
	v_cndmask_b32_e32 v5, v95, v5, vcc
	v_add_f32_e32 v5, 1.0, v5
	v_div_scale_f32 v8, s[54:55], v5, v5, v4
	v_rcp_f32_e32 v23, v8
	v_div_scale_f32 v61, vcc, v4, v5, v4
	v_fma_f32 v65, -v8, v23, 1.0
	v_fmac_f32_e32 v23, v65, v23
	v_mul_f32_e32 v65, v61, v23
	v_fma_f32 v66, -v8, v65, v61
	v_fmac_f32_e32 v65, v66, v23
	v_fma_f32 v8, -v8, v65, v61
	v_div_fmas_f32 v8, v8, v23, v65
	v_div_fixup_f32 v4, v8, v5, v4
	ds_write_b32 v2, v4 offset:1024
	s_waitcnt vmcnt(57)
	v_mov_b32_e32 v4, v216
	v_mul_f32_e32 v5, 0xbfb8aa3b, v4
	v_fma_f32 v8, v4, s67, -v5
	v_rndne_f32_e32 v23, v5
	v_fmac_f32_e32 v8, 0xb2a5705f, v4
	v_sub_f32_e32 v5, v5, v23
	v_add_f32_e32 v5, v5, v8
	v_cvt_i32_f32_e32 v23, v23
	v_exp_f32_e32 v5, v5
	v_cmp_nlt_f32_e32 vcc, s68, v4
	v_ldexp_f32 v5, v5, v23
	s_nop 0
	v_cndmask_b32_e32 v5, 0, v5, vcc
	v_cmp_ngt_f32_e32 vcc, s69, v4
	s_nop 1
	v_cndmask_b32_e32 v5, v95, v5, vcc
	v_add_f32_e32 v5, 1.0, v5
	v_div_scale_f32 v8, s[54:55], v5, v5, v4
	v_rcp_f32_e32 v23, v8
	v_div_scale_f32 v61, vcc, v4, v5, v4
	v_fma_f32 v65, -v8, v23, 1.0
	v_fmac_f32_e32 v23, v65, v23
	v_mul_f32_e32 v65, v61, v23
	v_fma_f32 v66, -v8, v65, v61
	v_fmac_f32_e32 v65, v66, v23
	v_fma_f32 v8, -v8, v65, v61
	v_div_fmas_f32 v8, v8, v23, v65
	v_div_fixup_f32 v4, v8, v5, v4
	ds_write_b32 v2, v4 offset:2048
	s_waitcnt vmcnt(56)
	v_mov_b32_e32 v4, v217
	v_mul_f32_e32 v5, 0xbfb8aa3b, v4
	v_fma_f32 v8, v4, s67, -v5
	v_rndne_f32_e32 v23, v5
	v_fmac_f32_e32 v8, 0xb2a5705f, v4
	v_sub_f32_e32 v5, v5, v23
	v_add_f32_e32 v5, v5, v8
	v_cvt_i32_f32_e32 v23, v23
	v_exp_f32_e32 v5, v5
	v_cmp_nlt_f32_e32 vcc, s68, v4
	v_ldexp_f32 v5, v5, v23
	s_nop 0
	v_cndmask_b32_e32 v5, 0, v5, vcc
	v_cmp_ngt_f32_e32 vcc, s69, v4
	s_nop 1
	v_cndmask_b32_e32 v5, v95, v5, vcc
	v_add_f32_e32 v5, 1.0, v5
	v_div_scale_f32 v8, s[54:55], v5, v5, v4
	v_rcp_f32_e32 v23, v8
	v_div_scale_f32 v61, vcc, v4, v5, v4
	v_fma_f32 v65, -v8, v23, 1.0
	v_fmac_f32_e32 v23, v65, v23
	v_mul_f32_e32 v65, v61, v23
	v_fma_f32 v66, -v8, v65, v61
	v_fmac_f32_e32 v65, v66, v23
	v_fma_f32 v8, -v8, v65, v61
	v_div_fmas_f32 v8, v8, v23, v65
	v_div_fixup_f32 v4, v8, v5, v4
	ds_write_b32 v2, v4 offset:3072
	s_waitcnt vmcnt(55)
	v_mov_b32_e32 v4, v218
	v_mul_f32_e32 v5, 0xbfb8aa3b, v4
	v_fma_f32 v8, v4, s67, -v5
	v_rndne_f32_e32 v23, v5
	v_fmac_f32_e32 v8, 0xb2a5705f, v4
	v_sub_f32_e32 v5, v5, v23
	v_add_f32_e32 v5, v5, v8
	v_cvt_i32_f32_e32 v23, v23
	v_exp_f32_e32 v5, v5
	v_cmp_nlt_f32_e32 vcc, s68, v4
	v_ldexp_f32 v5, v5, v23
	s_nop 0
	v_cndmask_b32_e32 v5, 0, v5, vcc
	v_cmp_ngt_f32_e32 vcc, s69, v4
	s_nop 1
	v_cndmask_b32_e32 v5, v95, v5, vcc
	v_add_f32_e32 v5, 1.0, v5
	v_div_scale_f32 v8, s[54:55], v5, v5, v4
	v_rcp_f32_e32 v23, v8
	v_div_scale_f32 v61, vcc, v4, v5, v4
	v_fma_f32 v65, -v8, v23, 1.0
	v_fmac_f32_e32 v23, v65, v23
	v_mul_f32_e32 v65, v61, v23
	v_fma_f32 v66, -v8, v65, v61
	v_fmac_f32_e32 v65, v66, v23
	v_fma_f32 v8, -v8, v65, v61
	v_div_fmas_f32 v8, v8, v23, v65
	v_div_fixup_f32 v4, v8, v5, v4
	ds_write_b32 v2, v4 offset:4096
	s_waitcnt vmcnt(54)
	v_mov_b32_e32 v4, v219
	v_mul_f32_e32 v5, 0xbfb8aa3b, v4
	v_fma_f32 v8, v4, s67, -v5
	v_rndne_f32_e32 v23, v5
	v_fmac_f32_e32 v8, 0xb2a5705f, v4
	v_sub_f32_e32 v5, v5, v23
	v_add_f32_e32 v5, v5, v8
	v_cvt_i32_f32_e32 v23, v23
	v_exp_f32_e32 v5, v5
	v_cmp_nlt_f32_e32 vcc, s68, v4
	v_ldexp_f32 v5, v5, v23
	s_nop 0
	v_cndmask_b32_e32 v5, 0, v5, vcc
	v_cmp_ngt_f32_e32 vcc, s69, v4
	s_nop 1
	v_cndmask_b32_e32 v5, v95, v5, vcc
	v_add_f32_e32 v5, 1.0, v5
	v_div_scale_f32 v8, s[54:55], v5, v5, v4
	v_rcp_f32_e32 v23, v8
	v_div_scale_f32 v61, vcc, v4, v5, v4
	v_fma_f32 v65, -v8, v23, 1.0
	v_fmac_f32_e32 v23, v65, v23
	v_mul_f32_e32 v65, v61, v23
	v_fma_f32 v66, -v8, v65, v61
	v_fmac_f32_e32 v65, v66, v23
	v_fma_f32 v8, -v8, v65, v61
	v_div_fmas_f32 v8, v8, v23, v65
	v_div_fixup_f32 v4, v8, v5, v4
	ds_write_b32 v2, v4 offset:5120
	s_waitcnt vmcnt(53)
	v_mov_b32_e32 v4, v220
	v_mul_f32_e32 v5, 0xbfb8aa3b, v4
	v_fma_f32 v8, v4, s67, -v5
	v_rndne_f32_e32 v23, v5
	v_fmac_f32_e32 v8, 0xb2a5705f, v4
	v_sub_f32_e32 v5, v5, v23
	v_add_f32_e32 v5, v5, v8
	v_cvt_i32_f32_e32 v23, v23
	v_exp_f32_e32 v5, v5
	v_cmp_nlt_f32_e32 vcc, s68, v4
	v_ldexp_f32 v5, v5, v23
	s_nop 0
	v_cndmask_b32_e32 v5, 0, v5, vcc
	v_cmp_ngt_f32_e32 vcc, s69, v4
	s_nop 1
	v_cndmask_b32_e32 v5, v95, v5, vcc
	v_add_f32_e32 v5, 1.0, v5
	v_div_scale_f32 v8, s[54:55], v5, v5, v4
	v_rcp_f32_e32 v23, v8
	v_div_scale_f32 v61, vcc, v4, v5, v4
	v_fma_f32 v65, -v8, v23, 1.0
	v_fmac_f32_e32 v23, v65, v23
	v_mul_f32_e32 v65, v61, v23
	v_fma_f32 v66, -v8, v65, v61
	v_fmac_f32_e32 v65, v66, v23
	v_fma_f32 v8, -v8, v65, v61
	v_div_fmas_f32 v8, v8, v23, v65
	v_div_fixup_f32 v4, v8, v5, v4
	ds_write_b32 v2, v4 offset:6144
	s_waitcnt vmcnt(52)
	v_mov_b32_e32 v4, v221
	v_mul_f32_e32 v5, 0xbfb8aa3b, v4
	v_fma_f32 v8, v4, s67, -v5
	v_rndne_f32_e32 v23, v5
	v_fmac_f32_e32 v8, 0xb2a5705f, v4
	v_sub_f32_e32 v5, v5, v23
	v_add_f32_e32 v5, v5, v8
	v_cvt_i32_f32_e32 v23, v23
	v_exp_f32_e32 v5, v5
	v_cmp_nlt_f32_e32 vcc, s68, v4
	v_ldexp_f32 v5, v5, v23
	s_nop 0
	v_cndmask_b32_e32 v5, 0, v5, vcc
	v_cmp_ngt_f32_e32 vcc, s69, v4
	s_nop 1
	v_cndmask_b32_e32 v5, v95, v5, vcc
	v_add_f32_e32 v5, 1.0, v5
	v_div_scale_f32 v8, s[54:55], v5, v5, v4
	v_rcp_f32_e32 v23, v8
	v_div_scale_f32 v61, vcc, v4, v5, v4
	v_fma_f32 v65, -v8, v23, 1.0
	v_fmac_f32_e32 v23, v65, v23
	v_mul_f32_e32 v65, v61, v23
	v_fma_f32 v66, -v8, v65, v61
	v_fmac_f32_e32 v65, v66, v23
	v_fma_f32 v8, -v8, v65, v61
	v_div_fmas_f32 v8, v8, v23, v65
	v_div_fixup_f32 v4, v8, v5, v4
	ds_write_b32 v2, v4 offset:7168
	s_waitcnt vmcnt(51)
	v_mov_b32_e32 v4, v222
	v_mul_f32_e32 v5, 0xbfb8aa3b, v4
	v_fma_f32 v8, v4, s67, -v5
	v_rndne_f32_e32 v23, v5
	v_fmac_f32_e32 v8, 0xb2a5705f, v4
	v_sub_f32_e32 v5, v5, v23
	v_add_f32_e32 v5, v5, v8
	v_cvt_i32_f32_e32 v23, v23
	v_exp_f32_e32 v5, v5
	v_cmp_nlt_f32_e32 vcc, s68, v4
	v_ldexp_f32 v5, v5, v23
	s_nop 0
	v_cndmask_b32_e32 v5, 0, v5, vcc
	v_cmp_ngt_f32_e32 vcc, s69, v4
	s_nop 1
	v_cndmask_b32_e32 v5, v95, v5, vcc
	v_add_f32_e32 v5, 1.0, v5
	v_div_scale_f32 v8, s[54:55], v5, v5, v4
	v_rcp_f32_e32 v23, v8
	v_div_scale_f32 v61, vcc, v4, v5, v4
	v_fma_f32 v65, -v8, v23, 1.0
	v_fmac_f32_e32 v23, v65, v23
	v_mul_f32_e32 v65, v61, v23
	v_fma_f32 v66, -v8, v65, v61
	v_fmac_f32_e32 v65, v66, v23
	v_fma_f32 v8, -v8, v65, v61
	v_div_fmas_f32 v8, v8, v23, v65
	v_div_fixup_f32 v4, v8, v5, v4
	ds_write_b32 v2, v4 offset:8192
	s_waitcnt vmcnt(50)
	v_mov_b32_e32 v4, v223
	v_mul_f32_e32 v5, 0xbfb8aa3b, v4
	v_fma_f32 v8, v4, s67, -v5
	v_rndne_f32_e32 v23, v5
	v_fmac_f32_e32 v8, 0xb2a5705f, v4
	v_sub_f32_e32 v5, v5, v23
	v_add_f32_e32 v5, v5, v8
	v_cvt_i32_f32_e32 v23, v23
	v_exp_f32_e32 v5, v5
	v_cmp_nlt_f32_e32 vcc, s68, v4
	v_ldexp_f32 v5, v5, v23
	s_nop 0
	v_cndmask_b32_e32 v5, 0, v5, vcc
	v_cmp_ngt_f32_e32 vcc, s69, v4
	s_nop 1
	v_cndmask_b32_e32 v5, v95, v5, vcc
	v_add_f32_e32 v5, 1.0, v5
	v_div_scale_f32 v8, s[54:55], v5, v5, v4
	v_rcp_f32_e32 v23, v8
	v_div_scale_f32 v61, vcc, v4, v5, v4
	v_fma_f32 v65, -v8, v23, 1.0
	v_fmac_f32_e32 v23, v65, v23
	v_mul_f32_e32 v65, v61, v23
	v_fma_f32 v66, -v8, v65, v61
	v_fmac_f32_e32 v65, v66, v23
	v_fma_f32 v8, -v8, v65, v61
	v_div_fmas_f32 v8, v8, v23, v65
	v_div_fixup_f32 v4, v8, v5, v4
	ds_write_b32 v2, v4 offset:9216
	s_waitcnt vmcnt(49)
	v_mov_b32_e32 v4, v224
	v_mul_f32_e32 v5, 0xbfb8aa3b, v4
	v_fma_f32 v8, v4, s67, -v5
	v_rndne_f32_e32 v23, v5
	v_fmac_f32_e32 v8, 0xb2a5705f, v4
	v_sub_f32_e32 v5, v5, v23
	v_add_f32_e32 v5, v5, v8
	v_cvt_i32_f32_e32 v23, v23
	v_exp_f32_e32 v5, v5
	v_cmp_nlt_f32_e32 vcc, s68, v4
	v_ldexp_f32 v5, v5, v23
	s_nop 0
	v_cndmask_b32_e32 v5, 0, v5, vcc
	v_cmp_ngt_f32_e32 vcc, s69, v4
	s_nop 1
	v_cndmask_b32_e32 v5, v95, v5, vcc
	v_add_f32_e32 v5, 1.0, v5
	v_div_scale_f32 v8, s[54:55], v5, v5, v4
	v_rcp_f32_e32 v23, v8
	v_div_scale_f32 v61, vcc, v4, v5, v4
	v_fma_f32 v65, -v8, v23, 1.0
	v_fmac_f32_e32 v23, v65, v23
	v_mul_f32_e32 v65, v61, v23
	v_fma_f32 v66, -v8, v65, v61
	v_fmac_f32_e32 v65, v66, v23
	v_fma_f32 v8, -v8, v65, v61
	v_div_fmas_f32 v8, v8, v23, v65
	v_div_fixup_f32 v4, v8, v5, v4
	ds_write_b32 v2, v4 offset:10240
	s_waitcnt vmcnt(48)
	v_mov_b32_e32 v4, v225
	v_mul_f32_e32 v5, 0xbfb8aa3b, v4
	v_fma_f32 v8, v4, s67, -v5
	v_rndne_f32_e32 v23, v5
	v_fmac_f32_e32 v8, 0xb2a5705f, v4
	v_sub_f32_e32 v5, v5, v23
	v_add_f32_e32 v5, v5, v8
	v_cvt_i32_f32_e32 v23, v23
	v_exp_f32_e32 v5, v5
	v_cmp_nlt_f32_e32 vcc, s68, v4
	v_ldexp_f32 v5, v5, v23
	s_nop 0
	v_cndmask_b32_e32 v5, 0, v5, vcc
	v_cmp_ngt_f32_e32 vcc, s69, v4
	s_nop 1
	v_cndmask_b32_e32 v5, v95, v5, vcc
	v_add_f32_e32 v5, 1.0, v5
	v_div_scale_f32 v8, s[54:55], v5, v5, v4
	v_rcp_f32_e32 v23, v8
	v_div_scale_f32 v61, vcc, v4, v5, v4
	v_fma_f32 v65, -v8, v23, 1.0
	v_fmac_f32_e32 v23, v65, v23
	v_mul_f32_e32 v65, v61, v23
	v_fma_f32 v66, -v8, v65, v61
	v_fmac_f32_e32 v65, v66, v23
	v_fma_f32 v8, -v8, v65, v61
	v_div_fmas_f32 v8, v8, v23, v65
	v_div_fixup_f32 v4, v8, v5, v4
	ds_write_b32 v2, v4 offset:11264
	s_waitcnt vmcnt(47)
	v_mov_b32_e32 v4, v226
	v_mul_f32_e32 v5, 0xbfb8aa3b, v4
	v_fma_f32 v8, v4, s67, -v5
	v_rndne_f32_e32 v23, v5
	v_fmac_f32_e32 v8, 0xb2a5705f, v4
	v_sub_f32_e32 v5, v5, v23
	v_add_f32_e32 v5, v5, v8
	v_cvt_i32_f32_e32 v23, v23
	v_exp_f32_e32 v5, v5
	v_cmp_nlt_f32_e32 vcc, s68, v4
	v_ldexp_f32 v5, v5, v23
	s_nop 0
	v_cndmask_b32_e32 v5, 0, v5, vcc
	v_cmp_ngt_f32_e32 vcc, s69, v4
	s_nop 1
	v_cndmask_b32_e32 v5, v95, v5, vcc
	v_add_f32_e32 v5, 1.0, v5
	v_div_scale_f32 v8, s[54:55], v5, v5, v4
	v_rcp_f32_e32 v23, v8
	v_div_scale_f32 v61, vcc, v4, v5, v4
	v_fma_f32 v65, -v8, v23, 1.0
	v_fmac_f32_e32 v23, v65, v23
	v_mul_f32_e32 v65, v61, v23
	v_fma_f32 v66, -v8, v65, v61
	v_fmac_f32_e32 v65, v66, v23
	v_fma_f32 v8, -v8, v65, v61
	v_div_fmas_f32 v8, v8, v23, v65
	v_div_fixup_f32 v4, v8, v5, v4
	ds_write_b32 v2, v4 offset:12288
	s_waitcnt vmcnt(46)
	v_mov_b32_e32 v4, v227
	v_mul_f32_e32 v5, 0xbfb8aa3b, v4
	v_fma_f32 v8, v4, s67, -v5
	v_rndne_f32_e32 v23, v5
	v_fmac_f32_e32 v8, 0xb2a5705f, v4
	v_sub_f32_e32 v5, v5, v23
	v_add_f32_e32 v5, v5, v8
	v_cvt_i32_f32_e32 v23, v23
	v_exp_f32_e32 v5, v5
	v_cmp_nlt_f32_e32 vcc, s68, v4
	v_ldexp_f32 v5, v5, v23
	s_nop 0
	v_cndmask_b32_e32 v5, 0, v5, vcc
	v_cmp_ngt_f32_e32 vcc, s69, v4
	s_nop 1
	v_cndmask_b32_e32 v5, v95, v5, vcc
	v_add_f32_e32 v5, 1.0, v5
	v_div_scale_f32 v8, s[54:55], v5, v5, v4
	v_rcp_f32_e32 v23, v8
	v_div_scale_f32 v61, vcc, v4, v5, v4
	v_fma_f32 v65, -v8, v23, 1.0
	v_fmac_f32_e32 v23, v65, v23
	v_mul_f32_e32 v65, v61, v23
	v_fma_f32 v66, -v8, v65, v61
	v_fmac_f32_e32 v65, v66, v23
	v_fma_f32 v8, -v8, v65, v61
	v_div_fmas_f32 v8, v8, v23, v65
	v_div_fixup_f32 v4, v8, v5, v4
	ds_write_b32 v2, v4 offset:13312
	s_waitcnt vmcnt(45)
	v_mov_b32_e32 v4, v228
	v_mul_f32_e32 v5, 0xbfb8aa3b, v4
	v_fma_f32 v8, v4, s67, -v5
	v_rndne_f32_e32 v23, v5
	v_fmac_f32_e32 v8, 0xb2a5705f, v4
	v_sub_f32_e32 v5, v5, v23
	v_add_f32_e32 v5, v5, v8
	v_cvt_i32_f32_e32 v23, v23
	v_exp_f32_e32 v5, v5
	v_cmp_nlt_f32_e32 vcc, s68, v4
	v_ldexp_f32 v5, v5, v23
	s_nop 0
	v_cndmask_b32_e32 v5, 0, v5, vcc
	v_cmp_ngt_f32_e32 vcc, s69, v4
	s_nop 1
	v_cndmask_b32_e32 v5, v95, v5, vcc
	v_add_f32_e32 v5, 1.0, v5
	v_div_scale_f32 v8, s[54:55], v5, v5, v4
	v_rcp_f32_e32 v23, v8
	v_div_scale_f32 v61, vcc, v4, v5, v4
	v_fma_f32 v65, -v8, v23, 1.0
	v_fmac_f32_e32 v23, v65, v23
	v_mul_f32_e32 v65, v61, v23
	v_fma_f32 v66, -v8, v65, v61
	v_fmac_f32_e32 v65, v66, v23
	v_fma_f32 v8, -v8, v65, v61
	v_div_fmas_f32 v8, v8, v23, v65
	v_div_fixup_f32 v4, v8, v5, v4
	ds_write_b32 v2, v4 offset:14336
	s_waitcnt vmcnt(44)
	v_mov_b32_e32 v4, v229
	v_mul_f32_e32 v5, 0xbfb8aa3b, v4
	v_fma_f32 v8, v4, s67, -v5
	v_rndne_f32_e32 v23, v5
	v_fmac_f32_e32 v8, 0xb2a5705f, v4
	v_sub_f32_e32 v5, v5, v23
	v_add_f32_e32 v5, v5, v8
	v_cvt_i32_f32_e32 v23, v23
	v_exp_f32_e32 v5, v5
	v_cmp_nlt_f32_e32 vcc, s68, v4
	v_ldexp_f32 v5, v5, v23
	s_nop 0
	v_cndmask_b32_e32 v5, 0, v5, vcc
	v_cmp_ngt_f32_e32 vcc, s69, v4
	s_nop 1
	v_cndmask_b32_e32 v5, v95, v5, vcc
	v_add_f32_e32 v5, 1.0, v5
	v_div_scale_f32 v8, s[54:55], v5, v5, v4
	v_rcp_f32_e32 v23, v8
	v_div_scale_f32 v61, vcc, v4, v5, v4
	v_fma_f32 v65, -v8, v23, 1.0
	v_fmac_f32_e32 v23, v65, v23
	v_mul_f32_e32 v65, v61, v23
	v_fma_f32 v66, -v8, v65, v61
	v_fmac_f32_e32 v65, v66, v23
	v_fma_f32 v8, -v8, v65, v61
	v_div_fmas_f32 v8, v8, v23, v65
	v_div_fixup_f32 v4, v8, v5, v4
	ds_write_b32 v2, v4 offset:15360
	s_waitcnt vmcnt(43)
	v_mov_b32_e32 v4, v230
	v_mul_f32_e32 v5, 0xbfb8aa3b, v4
	v_fma_f32 v8, v4, s67, -v5
	v_rndne_f32_e32 v23, v5
	v_fmac_f32_e32 v8, 0xb2a5705f, v4
	v_sub_f32_e32 v5, v5, v23
	v_add_f32_e32 v5, v5, v8
	v_cvt_i32_f32_e32 v23, v23
	v_exp_f32_e32 v5, v5
	v_cmp_nlt_f32_e32 vcc, s68, v4
	v_ldexp_f32 v5, v5, v23
	s_nop 0
	v_cndmask_b32_e32 v5, 0, v5, vcc
	v_cmp_ngt_f32_e32 vcc, s69, v4
	s_nop 1
	v_cndmask_b32_e32 v5, v95, v5, vcc
	v_add_f32_e32 v5, 1.0, v5
	v_div_scale_f32 v8, s[54:55], v5, v5, v4
	v_rcp_f32_e32 v23, v8
	v_div_scale_f32 v61, vcc, v4, v5, v4
	v_fma_f32 v65, -v8, v23, 1.0
	v_fmac_f32_e32 v23, v65, v23
	v_mul_f32_e32 v65, v61, v23
	v_fma_f32 v66, -v8, v65, v61
	v_fmac_f32_e32 v65, v66, v23
	v_fma_f32 v8, -v8, v65, v61
	v_div_fmas_f32 v8, v8, v23, v65
	v_div_fixup_f32 v4, v8, v5, v4
	ds_write_b32 v2, v4 offset:16384
	s_waitcnt vmcnt(42)
	v_mov_b32_e32 v4, v231
	v_mul_f32_e32 v5, 0xbfb8aa3b, v4
	v_fma_f32 v8, v4, s67, -v5
	v_rndne_f32_e32 v23, v5
	v_fmac_f32_e32 v8, 0xb2a5705f, v4
	v_sub_f32_e32 v5, v5, v23
	v_add_f32_e32 v5, v5, v8
	v_cvt_i32_f32_e32 v23, v23
	v_exp_f32_e32 v5, v5
	v_cmp_nlt_f32_e32 vcc, s68, v4
	v_ldexp_f32 v5, v5, v23
	s_nop 0
	v_cndmask_b32_e32 v5, 0, v5, vcc
	v_cmp_ngt_f32_e32 vcc, s69, v4
	s_nop 1
	v_cndmask_b32_e32 v5, v95, v5, vcc
	v_add_f32_e32 v5, 1.0, v5
	v_div_scale_f32 v8, s[54:55], v5, v5, v4
	v_rcp_f32_e32 v23, v8
	v_div_scale_f32 v61, vcc, v4, v5, v4
	v_fma_f32 v65, -v8, v23, 1.0
	v_fmac_f32_e32 v23, v65, v23
	v_mul_f32_e32 v65, v61, v23
	v_fma_f32 v66, -v8, v65, v61
	v_fmac_f32_e32 v65, v66, v23
	v_fma_f32 v8, -v8, v65, v61
	v_div_fmas_f32 v8, v8, v23, v65
	v_div_fixup_f32 v4, v8, v5, v4
	ds_write_b32 v2, v4 offset:17408
	s_waitcnt vmcnt(41)
	v_mov_b32_e32 v4, v232
	v_mul_f32_e32 v5, 0xbfb8aa3b, v4
	v_fma_f32 v8, v4, s67, -v5
	v_rndne_f32_e32 v23, v5
	v_fmac_f32_e32 v8, 0xb2a5705f, v4
	v_sub_f32_e32 v5, v5, v23
	v_add_f32_e32 v5, v5, v8
	v_cvt_i32_f32_e32 v23, v23
	v_exp_f32_e32 v5, v5
	v_cmp_nlt_f32_e32 vcc, s68, v4
	v_ldexp_f32 v5, v5, v23
	s_nop 0
	v_cndmask_b32_e32 v5, 0, v5, vcc
	v_cmp_ngt_f32_e32 vcc, s69, v4
	s_nop 1
	v_cndmask_b32_e32 v5, v95, v5, vcc
	v_add_f32_e32 v5, 1.0, v5
	v_div_scale_f32 v8, s[54:55], v5, v5, v4
	v_rcp_f32_e32 v23, v8
	v_div_scale_f32 v61, vcc, v4, v5, v4
	v_fma_f32 v65, -v8, v23, 1.0
	v_fmac_f32_e32 v23, v65, v23
	v_mul_f32_e32 v65, v61, v23
	v_fma_f32 v66, -v8, v65, v61
	v_fmac_f32_e32 v65, v66, v23
	v_fma_f32 v8, -v8, v65, v61
	v_div_fmas_f32 v8, v8, v23, v65
	v_div_fixup_f32 v4, v8, v5, v4
	ds_write_b32 v2, v4 offset:18432
	s_waitcnt vmcnt(40)
	v_mov_b32_e32 v4, v233
	v_mul_f32_e32 v5, 0xbfb8aa3b, v4
	v_fma_f32 v8, v4, s67, -v5
	v_rndne_f32_e32 v23, v5
	v_fmac_f32_e32 v8, 0xb2a5705f, v4
	v_sub_f32_e32 v5, v5, v23
	v_add_f32_e32 v5, v5, v8
	v_cvt_i32_f32_e32 v23, v23
	v_exp_f32_e32 v5, v5
	v_cmp_nlt_f32_e32 vcc, s68, v4
	v_ldexp_f32 v5, v5, v23
	s_nop 0
	v_cndmask_b32_e32 v5, 0, v5, vcc
	v_cmp_ngt_f32_e32 vcc, s69, v4
	s_nop 1
	v_cndmask_b32_e32 v5, v95, v5, vcc
	v_add_f32_e32 v5, 1.0, v5
	v_div_scale_f32 v8, s[54:55], v5, v5, v4
	v_rcp_f32_e32 v23, v8
	v_div_scale_f32 v61, vcc, v4, v5, v4
	v_fma_f32 v65, -v8, v23, 1.0
	v_fmac_f32_e32 v23, v65, v23
	v_mul_f32_e32 v65, v61, v23
	v_fma_f32 v66, -v8, v65, v61
	v_fmac_f32_e32 v65, v66, v23
	v_fma_f32 v8, -v8, v65, v61
	v_div_fmas_f32 v8, v8, v23, v65
	v_div_fixup_f32 v4, v8, v5, v4
	ds_write_b32 v2, v4 offset:19456
	s_waitcnt vmcnt(39)
	v_mov_b32_e32 v4, v234
	v_mul_f32_e32 v5, 0xbfb8aa3b, v4
	v_fma_f32 v8, v4, s67, -v5
	v_rndne_f32_e32 v23, v5
	v_fmac_f32_e32 v8, 0xb2a5705f, v4
	v_sub_f32_e32 v5, v5, v23
	v_add_f32_e32 v5, v5, v8
	v_cvt_i32_f32_e32 v23, v23
	v_exp_f32_e32 v5, v5
	v_cmp_nlt_f32_e32 vcc, s68, v4
	v_ldexp_f32 v5, v5, v23
	s_nop 0
	v_cndmask_b32_e32 v5, 0, v5, vcc
	v_cmp_ngt_f32_e32 vcc, s69, v4
	s_nop 1
	v_cndmask_b32_e32 v5, v95, v5, vcc
	v_add_f32_e32 v5, 1.0, v5
	v_div_scale_f32 v8, s[54:55], v5, v5, v4
	v_rcp_f32_e32 v23, v8
	v_div_scale_f32 v61, vcc, v4, v5, v4
	v_fma_f32 v65, -v8, v23, 1.0
	v_fmac_f32_e32 v23, v65, v23
	v_mul_f32_e32 v65, v61, v23
	v_fma_f32 v66, -v8, v65, v61
	v_fmac_f32_e32 v65, v66, v23
	v_fma_f32 v8, -v8, v65, v61
	v_div_fmas_f32 v8, v8, v23, v65
	v_div_fixup_f32 v4, v8, v5, v4
	ds_write_b32 v2, v4 offset:20480
	s_waitcnt vmcnt(38)
	v_mov_b32_e32 v4, v235
	v_mul_f32_e32 v5, 0xbfb8aa3b, v4
	v_fma_f32 v8, v4, s67, -v5
	v_rndne_f32_e32 v23, v5
	v_fmac_f32_e32 v8, 0xb2a5705f, v4
	v_sub_f32_e32 v5, v5, v23
	v_add_f32_e32 v5, v5, v8
	v_cvt_i32_f32_e32 v23, v23
	v_exp_f32_e32 v5, v5
	v_cmp_nlt_f32_e32 vcc, s68, v4
	v_ldexp_f32 v5, v5, v23
	s_nop 0
	v_cndmask_b32_e32 v5, 0, v5, vcc
	v_cmp_ngt_f32_e32 vcc, s69, v4
	s_nop 1
	v_cndmask_b32_e32 v5, v95, v5, vcc
	v_add_f32_e32 v5, 1.0, v5
	v_div_scale_f32 v8, s[54:55], v5, v5, v4
	v_rcp_f32_e32 v23, v8
	v_div_scale_f32 v61, vcc, v4, v5, v4
	v_fma_f32 v65, -v8, v23, 1.0
	v_fmac_f32_e32 v23, v65, v23
	v_mul_f32_e32 v65, v61, v23
	v_fma_f32 v66, -v8, v65, v61
	v_fmac_f32_e32 v65, v66, v23
	v_fma_f32 v8, -v8, v65, v61
	v_div_fmas_f32 v8, v8, v23, v65
	v_div_fixup_f32 v4, v8, v5, v4
	ds_write_b32 v2, v4 offset:21504
	s_waitcnt vmcnt(37)
	v_mov_b32_e32 v4, v236
	v_mul_f32_e32 v5, 0xbfb8aa3b, v4
	v_fma_f32 v8, v4, s67, -v5
	v_rndne_f32_e32 v23, v5
	v_fmac_f32_e32 v8, 0xb2a5705f, v4
	v_sub_f32_e32 v5, v5, v23
	v_add_f32_e32 v5, v5, v8
	v_cvt_i32_f32_e32 v23, v23
	v_exp_f32_e32 v5, v5
	v_cmp_nlt_f32_e32 vcc, s68, v4
	v_ldexp_f32 v5, v5, v23
	s_nop 0
	v_cndmask_b32_e32 v5, 0, v5, vcc
	v_cmp_ngt_f32_e32 vcc, s69, v4
	s_nop 1
	v_cndmask_b32_e32 v5, v95, v5, vcc
	v_add_f32_e32 v5, 1.0, v5
	v_div_scale_f32 v8, s[54:55], v5, v5, v4
	v_rcp_f32_e32 v23, v8
	v_div_scale_f32 v61, vcc, v4, v5, v4
	v_fma_f32 v65, -v8, v23, 1.0
	v_fmac_f32_e32 v23, v65, v23
	v_mul_f32_e32 v65, v61, v23
	v_fma_f32 v66, -v8, v65, v61
	v_fmac_f32_e32 v65, v66, v23
	v_fma_f32 v8, -v8, v65, v61
	v_div_fmas_f32 v8, v8, v23, v65
	v_div_fixup_f32 v4, v8, v5, v4
	ds_write_b32 v2, v4 offset:22528
	s_waitcnt vmcnt(36)
	v_mov_b32_e32 v4, v237
	v_mul_f32_e32 v5, 0xbfb8aa3b, v4
	v_fma_f32 v8, v4, s67, -v5
	v_rndne_f32_e32 v23, v5
	v_fmac_f32_e32 v8, 0xb2a5705f, v4
	v_sub_f32_e32 v5, v5, v23
	v_add_f32_e32 v5, v5, v8
	v_cvt_i32_f32_e32 v23, v23
	v_exp_f32_e32 v5, v5
	v_cmp_nlt_f32_e32 vcc, s68, v4
	v_ldexp_f32 v5, v5, v23
	s_nop 0
	v_cndmask_b32_e32 v5, 0, v5, vcc
	v_cmp_ngt_f32_e32 vcc, s69, v4
	s_nop 1
	v_cndmask_b32_e32 v5, v95, v5, vcc
	v_add_f32_e32 v5, 1.0, v5
	v_div_scale_f32 v8, s[54:55], v5, v5, v4
	v_rcp_f32_e32 v23, v8
	v_div_scale_f32 v61, vcc, v4, v5, v4
	v_fma_f32 v65, -v8, v23, 1.0
	v_fmac_f32_e32 v23, v65, v23
	v_mul_f32_e32 v65, v61, v23
	v_fma_f32 v66, -v8, v65, v61
	v_fmac_f32_e32 v65, v66, v23
	v_fma_f32 v8, -v8, v65, v61
	v_div_fmas_f32 v8, v8, v23, v65
	v_div_fixup_f32 v4, v8, v5, v4
	ds_write_b32 v2, v4 offset:23552
	s_waitcnt vmcnt(35)
	v_mov_b32_e32 v4, v239
	v_mul_f32_e32 v5, 0xbfb8aa3b, v4
	v_fma_f32 v8, v4, s67, -v5
	v_rndne_f32_e32 v23, v5
	v_fmac_f32_e32 v8, 0xb2a5705f, v4
	v_sub_f32_e32 v5, v5, v23
	v_add_f32_e32 v5, v5, v8
	v_cvt_i32_f32_e32 v23, v23
	v_exp_f32_e32 v5, v5
	v_cmp_nlt_f32_e32 vcc, s68, v4
	v_ldexp_f32 v5, v5, v23
	s_nop 0
	v_cndmask_b32_e32 v5, 0, v5, vcc
	v_cmp_ngt_f32_e32 vcc, s69, v4
	s_nop 1
	v_cndmask_b32_e32 v5, v95, v5, vcc
	v_add_f32_e32 v5, 1.0, v5
	v_div_scale_f32 v8, s[54:55], v5, v5, v4
	v_rcp_f32_e32 v23, v8
	v_div_scale_f32 v61, vcc, v4, v5, v4
	v_fma_f32 v65, -v8, v23, 1.0
	v_fmac_f32_e32 v23, v65, v23
	v_mul_f32_e32 v65, v61, v23
	v_fma_f32 v66, -v8, v65, v61
	v_fmac_f32_e32 v65, v66, v23
	v_fma_f32 v8, -v8, v65, v61
	v_div_fmas_f32 v8, v8, v23, v65
	v_div_fixup_f32 v4, v8, v5, v4
	ds_write_b32 v2, v4 offset:24576
	s_waitcnt vmcnt(34)
	v_mov_b32_e32 v4, v240
	v_mul_f32_e32 v5, 0xbfb8aa3b, v4
	v_fma_f32 v8, v4, s67, -v5
	v_rndne_f32_e32 v23, v5
	v_fmac_f32_e32 v8, 0xb2a5705f, v4
	v_sub_f32_e32 v5, v5, v23
	v_add_f32_e32 v5, v5, v8
	v_cvt_i32_f32_e32 v23, v23
	v_exp_f32_e32 v5, v5
	v_cmp_nlt_f32_e32 vcc, s68, v4
	v_ldexp_f32 v5, v5, v23
	s_nop 0
	v_cndmask_b32_e32 v5, 0, v5, vcc
	v_cmp_ngt_f32_e32 vcc, s69, v4
	s_nop 1
	v_cndmask_b32_e32 v5, v95, v5, vcc
	v_add_f32_e32 v5, 1.0, v5
	v_div_scale_f32 v8, s[54:55], v5, v5, v4
	v_rcp_f32_e32 v23, v8
	v_div_scale_f32 v61, vcc, v4, v5, v4
	v_fma_f32 v65, -v8, v23, 1.0
	v_fmac_f32_e32 v23, v65, v23
	v_mul_f32_e32 v65, v61, v23
	v_fma_f32 v66, -v8, v65, v61
	v_fmac_f32_e32 v65, v66, v23
	v_fma_f32 v8, -v8, v65, v61
	v_div_fmas_f32 v8, v8, v23, v65
	v_div_fixup_f32 v4, v8, v5, v4
	ds_write_b32 v2, v4 offset:25600
	s_waitcnt vmcnt(33)
	v_mov_b32_e32 v4, v241
	v_mul_f32_e32 v5, 0xbfb8aa3b, v4
	v_fma_f32 v8, v4, s67, -v5
	v_rndne_f32_e32 v23, v5
	v_fmac_f32_e32 v8, 0xb2a5705f, v4
	v_sub_f32_e32 v5, v5, v23
	v_add_f32_e32 v5, v5, v8
	v_cvt_i32_f32_e32 v23, v23
	v_exp_f32_e32 v5, v5
	v_cmp_nlt_f32_e32 vcc, s68, v4
	v_ldexp_f32 v5, v5, v23
	s_nop 0
	v_cndmask_b32_e32 v5, 0, v5, vcc
	v_cmp_ngt_f32_e32 vcc, s69, v4
	s_nop 1
	v_cndmask_b32_e32 v5, v95, v5, vcc
	v_add_f32_e32 v5, 1.0, v5
	v_div_scale_f32 v8, s[54:55], v5, v5, v4
	v_rcp_f32_e32 v23, v8
	v_div_scale_f32 v61, vcc, v4, v5, v4
	v_fma_f32 v65, -v8, v23, 1.0
	v_fmac_f32_e32 v23, v65, v23
	v_mul_f32_e32 v65, v61, v23
	v_fma_f32 v66, -v8, v65, v61
	v_fmac_f32_e32 v65, v66, v23
	v_fma_f32 v8, -v8, v65, v61
	v_div_fmas_f32 v8, v8, v23, v65
	v_div_fixup_f32 v4, v8, v5, v4
	ds_write_b32 v2, v4 offset:26624
	s_waitcnt vmcnt(32)
	v_mov_b32_e32 v4, v242
	v_mul_f32_e32 v5, 0xbfb8aa3b, v4
	v_fma_f32 v8, v4, s67, -v5
	v_rndne_f32_e32 v23, v5
	v_fmac_f32_e32 v8, 0xb2a5705f, v4
	v_sub_f32_e32 v5, v5, v23
	v_add_f32_e32 v5, v5, v8
	v_cvt_i32_f32_e32 v23, v23
	v_exp_f32_e32 v5, v5
	v_cmp_nlt_f32_e32 vcc, s68, v4
	v_ldexp_f32 v5, v5, v23
	s_nop 0
	v_cndmask_b32_e32 v5, 0, v5, vcc
	v_cmp_ngt_f32_e32 vcc, s69, v4
	s_nop 1
	v_cndmask_b32_e32 v5, v95, v5, vcc
	v_add_f32_e32 v5, 1.0, v5
	v_div_scale_f32 v8, s[54:55], v5, v5, v4
	v_rcp_f32_e32 v23, v8
	v_div_scale_f32 v61, vcc, v4, v5, v4
	v_fma_f32 v65, -v8, v23, 1.0
	v_fmac_f32_e32 v23, v65, v23
	v_mul_f32_e32 v65, v61, v23
	v_fma_f32 v66, -v8, v65, v61
	v_fmac_f32_e32 v65, v66, v23
	v_fma_f32 v8, -v8, v65, v61
	v_div_fmas_f32 v8, v8, v23, v65
	v_div_fixup_f32 v4, v8, v5, v4
	ds_write_b32 v2, v4 offset:27648
	s_waitcnt vmcnt(31)
	v_mov_b32_e32 v4, v243
	v_mul_f32_e32 v5, 0xbfb8aa3b, v4
	v_fma_f32 v8, v4, s67, -v5
	v_rndne_f32_e32 v23, v5
	v_fmac_f32_e32 v8, 0xb2a5705f, v4
	v_sub_f32_e32 v5, v5, v23
	v_add_f32_e32 v5, v5, v8
	v_cvt_i32_f32_e32 v23, v23
	v_exp_f32_e32 v5, v5
	v_cmp_nlt_f32_e32 vcc, s68, v4
	v_ldexp_f32 v5, v5, v23
	s_nop 0
	v_cndmask_b32_e32 v5, 0, v5, vcc
	v_cmp_ngt_f32_e32 vcc, s69, v4
	s_nop 1
	v_cndmask_b32_e32 v5, v95, v5, vcc
	v_add_f32_e32 v5, 1.0, v5
	v_div_scale_f32 v8, s[54:55], v5, v5, v4
	v_rcp_f32_e32 v23, v8
	v_div_scale_f32 v61, vcc, v4, v5, v4
	v_fma_f32 v65, -v8, v23, 1.0
	v_fmac_f32_e32 v23, v65, v23
	v_mul_f32_e32 v65, v61, v23
	v_fma_f32 v66, -v8, v65, v61
	v_fmac_f32_e32 v65, v66, v23
	v_fma_f32 v8, -v8, v65, v61
	v_div_fmas_f32 v8, v8, v23, v65
	v_div_fixup_f32 v4, v8, v5, v4
	ds_write_b32 v2, v4 offset:28672
	s_waitcnt vmcnt(30)
	v_mov_b32_e32 v4, v244
	v_mul_f32_e32 v5, 0xbfb8aa3b, v4
	v_fma_f32 v8, v4, s67, -v5
	v_rndne_f32_e32 v23, v5
	v_fmac_f32_e32 v8, 0xb2a5705f, v4
	v_sub_f32_e32 v5, v5, v23
	v_add_f32_e32 v5, v5, v8
	v_cvt_i32_f32_e32 v23, v23
	v_exp_f32_e32 v5, v5
	v_cmp_nlt_f32_e32 vcc, s68, v4
	v_ldexp_f32 v5, v5, v23
	s_nop 0
	v_cndmask_b32_e32 v5, 0, v5, vcc
	v_cmp_ngt_f32_e32 vcc, s69, v4
	s_nop 1
	v_cndmask_b32_e32 v5, v95, v5, vcc
	v_add_f32_e32 v5, 1.0, v5
	v_div_scale_f32 v8, s[54:55], v5, v5, v4
	v_rcp_f32_e32 v23, v8
	v_div_scale_f32 v61, vcc, v4, v5, v4
	v_fma_f32 v65, -v8, v23, 1.0
	v_fmac_f32_e32 v23, v65, v23
	v_mul_f32_e32 v65, v61, v23
	v_fma_f32 v66, -v8, v65, v61
	v_fmac_f32_e32 v65, v66, v23
	v_fma_f32 v8, -v8, v65, v61
	v_div_fmas_f32 v8, v8, v23, v65
	v_div_fixup_f32 v4, v8, v5, v4
	ds_write_b32 v2, v4 offset:29696
	s_waitcnt vmcnt(29)
	v_mov_b32_e32 v4, v245
	v_mul_f32_e32 v5, 0xbfb8aa3b, v4
	v_fma_f32 v8, v4, s67, -v5
	v_rndne_f32_e32 v23, v5
	v_fmac_f32_e32 v8, 0xb2a5705f, v4
	v_sub_f32_e32 v5, v5, v23
	v_add_f32_e32 v5, v5, v8
	v_cvt_i32_f32_e32 v23, v23
	v_exp_f32_e32 v5, v5
	v_cmp_nlt_f32_e32 vcc, s68, v4
	v_ldexp_f32 v5, v5, v23
	s_nop 0
	v_cndmask_b32_e32 v5, 0, v5, vcc
	v_cmp_ngt_f32_e32 vcc, s69, v4
	s_nop 1
	v_cndmask_b32_e32 v5, v95, v5, vcc
	v_add_f32_e32 v5, 1.0, v5
	v_div_scale_f32 v8, s[54:55], v5, v5, v4
	v_rcp_f32_e32 v23, v8
	v_div_scale_f32 v61, vcc, v4, v5, v4
	v_fma_f32 v65, -v8, v23, 1.0
	v_fmac_f32_e32 v23, v65, v23
	v_mul_f32_e32 v65, v61, v23
	v_fma_f32 v66, -v8, v65, v61
	v_fmac_f32_e32 v65, v66, v23
	v_fma_f32 v8, -v8, v65, v61
	v_div_fmas_f32 v8, v8, v23, v65
	v_div_fixup_f32 v4, v8, v5, v4
	ds_write_b32 v2, v4 offset:30720
	s_waitcnt vmcnt(28)
	v_mov_b32_e32 v4, v246
	v_mul_f32_e32 v5, 0xbfb8aa3b, v4
	v_fma_f32 v8, v4, s67, -v5
	v_rndne_f32_e32 v23, v5
	v_fmac_f32_e32 v8, 0xb2a5705f, v4
	v_sub_f32_e32 v5, v5, v23
	v_add_f32_e32 v5, v5, v8
	v_cvt_i32_f32_e32 v23, v23
	v_exp_f32_e32 v5, v5
	v_cmp_nlt_f32_e32 vcc, s68, v4
	v_ldexp_f32 v5, v5, v23
	s_nop 0
	v_cndmask_b32_e32 v5, 0, v5, vcc
	v_cmp_ngt_f32_e32 vcc, s69, v4
	s_nop 1
	v_cndmask_b32_e32 v5, v95, v5, vcc
	v_add_f32_e32 v5, 1.0, v5
	v_div_scale_f32 v8, s[54:55], v5, v5, v4
	v_rcp_f32_e32 v23, v8
	v_div_scale_f32 v61, vcc, v4, v5, v4
	v_fma_f32 v65, -v8, v23, 1.0
	v_fmac_f32_e32 v23, v65, v23
	v_mul_f32_e32 v65, v61, v23
	v_fma_f32 v66, -v8, v65, v61
	v_fmac_f32_e32 v65, v66, v23
	v_fma_f32 v8, -v8, v65, v61
	v_div_fmas_f32 v8, v8, v23, v65
	v_div_fixup_f32 v4, v8, v5, v4
	ds_write_b32 v2, v4 offset:31744
	s_waitcnt vmcnt(27)
	v_mov_b32_e32 v4, v247
	v_mul_f32_e32 v5, 0xbfb8aa3b, v4
	v_fma_f32 v8, v4, s67, -v5
	v_rndne_f32_e32 v23, v5
	v_fmac_f32_e32 v8, 0xb2a5705f, v4
	v_sub_f32_e32 v5, v5, v23
	v_add_f32_e32 v5, v5, v8
	v_cvt_i32_f32_e32 v23, v23
	v_exp_f32_e32 v5, v5
	v_cmp_nlt_f32_e32 vcc, s68, v4
	v_ldexp_f32 v5, v5, v23
	s_nop 0
	v_cndmask_b32_e32 v5, 0, v5, vcc
	v_cmp_ngt_f32_e32 vcc, s69, v4
	s_nop 1
	v_cndmask_b32_e32 v5, v95, v5, vcc
	v_add_f32_e32 v5, 1.0, v5
	v_div_scale_f32 v8, s[54:55], v5, v5, v4
	v_rcp_f32_e32 v23, v8
	v_div_scale_f32 v61, vcc, v4, v5, v4
	v_fma_f32 v65, -v8, v23, 1.0
	v_fmac_f32_e32 v23, v65, v23
	v_mul_f32_e32 v65, v61, v23
	v_fma_f32 v66, -v8, v65, v61
	v_fmac_f32_e32 v65, v66, v23
	v_fma_f32 v8, -v8, v65, v61
	v_div_fmas_f32 v8, v8, v23, v65
	v_div_fixup_f32 v4, v8, v5, v4
	ds_write_b32 v2, v4 offset:32768
	s_waitcnt vmcnt(26)
	v_mov_b32_e32 v4, v248
	v_mul_f32_e32 v5, 0xbfb8aa3b, v4
	v_fma_f32 v8, v4, s67, -v5
	v_rndne_f32_e32 v23, v5
	v_fmac_f32_e32 v8, 0xb2a5705f, v4
	v_sub_f32_e32 v5, v5, v23
	v_add_f32_e32 v5, v5, v8
	v_cvt_i32_f32_e32 v23, v23
	v_exp_f32_e32 v5, v5
	v_cmp_nlt_f32_e32 vcc, s68, v4
	v_ldexp_f32 v5, v5, v23
	s_nop 0
	v_cndmask_b32_e32 v5, 0, v5, vcc
	v_cmp_ngt_f32_e32 vcc, s69, v4
	s_nop 1
	v_cndmask_b32_e32 v5, v95, v5, vcc
	v_add_f32_e32 v5, 1.0, v5
	v_div_scale_f32 v8, s[54:55], v5, v5, v4
	v_rcp_f32_e32 v23, v8
	v_div_scale_f32 v61, vcc, v4, v5, v4
	v_fma_f32 v65, -v8, v23, 1.0
	v_fmac_f32_e32 v23, v65, v23
	v_mul_f32_e32 v65, v61, v23
	v_fma_f32 v66, -v8, v65, v61
	v_fmac_f32_e32 v65, v66, v23
	v_fma_f32 v8, -v8, v65, v61
	v_div_fmas_f32 v8, v8, v23, v65
	v_div_fixup_f32 v4, v8, v5, v4
	ds_write_b32 v2, v4 offset:33792
	s_waitcnt vmcnt(25)
	v_mov_b32_e32 v4, v249
	v_mul_f32_e32 v5, 0xbfb8aa3b, v4
	v_fma_f32 v8, v4, s67, -v5
	v_rndne_f32_e32 v23, v5
	v_fmac_f32_e32 v8, 0xb2a5705f, v4
	v_sub_f32_e32 v5, v5, v23
	v_add_f32_e32 v5, v5, v8
	v_cvt_i32_f32_e32 v23, v23
	v_exp_f32_e32 v5, v5
	v_cmp_nlt_f32_e32 vcc, s68, v4
	v_ldexp_f32 v5, v5, v23
	s_nop 0
	v_cndmask_b32_e32 v5, 0, v5, vcc
	v_cmp_ngt_f32_e32 vcc, s69, v4
	s_nop 1
	v_cndmask_b32_e32 v5, v95, v5, vcc
	v_add_f32_e32 v5, 1.0, v5
	v_div_scale_f32 v8, s[54:55], v5, v5, v4
	v_rcp_f32_e32 v23, v8
	v_div_scale_f32 v61, vcc, v4, v5, v4
	v_fma_f32 v65, -v8, v23, 1.0
	v_fmac_f32_e32 v23, v65, v23
	v_mul_f32_e32 v65, v61, v23
	v_fma_f32 v66, -v8, v65, v61
	v_fmac_f32_e32 v65, v66, v23
	v_fma_f32 v8, -v8, v65, v61
	v_div_fmas_f32 v8, v8, v23, v65
	v_div_fixup_f32 v4, v8, v5, v4
	ds_write_b32 v2, v4 offset:34816
	s_waitcnt vmcnt(24)
	v_mov_b32_e32 v4, v250
	v_mul_f32_e32 v5, 0xbfb8aa3b, v4
	v_fma_f32 v8, v4, s67, -v5
	v_rndne_f32_e32 v23, v5
	v_fmac_f32_e32 v8, 0xb2a5705f, v4
	v_sub_f32_e32 v5, v5, v23
	v_add_f32_e32 v5, v5, v8
	v_cvt_i32_f32_e32 v23, v23
	v_exp_f32_e32 v5, v5
	v_cmp_nlt_f32_e32 vcc, s68, v4
	v_ldexp_f32 v5, v5, v23
	s_nop 0
	v_cndmask_b32_e32 v5, 0, v5, vcc
	v_cmp_ngt_f32_e32 vcc, s69, v4
	s_nop 1
	v_cndmask_b32_e32 v5, v95, v5, vcc
	v_add_f32_e32 v5, 1.0, v5
	v_div_scale_f32 v8, s[54:55], v5, v5, v4
	v_rcp_f32_e32 v23, v8
	v_div_scale_f32 v61, vcc, v4, v5, v4
	v_fma_f32 v65, -v8, v23, 1.0
	v_fmac_f32_e32 v23, v65, v23
	v_mul_f32_e32 v65, v61, v23
	v_fma_f32 v66, -v8, v65, v61
	v_fmac_f32_e32 v65, v66, v23
	v_fma_f32 v8, -v8, v65, v61
	v_div_fmas_f32 v8, v8, v23, v65
	v_div_fixup_f32 v4, v8, v5, v4
	ds_write_b32 v2, v4 offset:35840
	s_or_b64 exec, exec, s[52:53]
	v_mov_b32_e32 v2, s72
	s_waitcnt lgkmcnt(0)
	s_barrier
	ds_read_b64 v[2:3], v2
	v_mov_b32_e32 v61, v9
	v_mov_b32_e32 v4, 0
	s_mov_b64 s[52:53], 0
	v_mov_b32_e32 v8, v81
	s_waitcnt lgkmcnt(0)
	v_add_co_u32_e32 v2, vcc, v2, v10
	v_addc_co_u32_e32 v3, vcc, v3, v11, vcc
	v_lshl_add_u64 v[2:3], v[60:61], 2, v[2:3]
	v_mov_b32_e32 v5, v4
	v_mov_b32_e32 v68, v4
	v_mov_b32_e32 v69, v4
	v_mov_b32_e32 v70, v4
	v_mov_b32_e32 v71, v4
	v_mov_b32_e32 v72, v4
	v_mov_b32_e32 v73, v4
	v_mov_b32_e32 v23, v4
	v_mov_b32_e32 v196, 0
	v_mov_b32_e32 v197, 0
	v_mov_b32_e32 v198, 0
	v_mov_b32_e32 v199, 0
	v_mov_b32_e32 v200, 0
	v_mov_b32_e32 v201, 0
	v_mov_b32_e32 v202, 0
	v_mov_b32_e32 v203, 0
	v_mov_b32_e32 v204, 0
	v_mov_b32_e32 v205, 0
	v_mov_b32_e32 v206, 0
	v_mov_b32_e32 v207, 0
	v_mov_b32_e32 v208, 0
	v_mov_b32_e32 v209, 0
	v_mov_b32_e32 v210, 0
	v_mov_b32_e32 v211, 0
	v_mov_b32_e32 v212, 0
	v_mov_b32_e32 v213, 0
	global_load_dword v174, v[194:195], off
	v_add_co_u32_e32 v194, vcc, 0x6000, v194
	v_addc_co_u32_e32 v195, vcc, 0, v195, vcc
	global_load_dword v175, v[194:195], off
	v_add_co_u32_e32 v194, vcc, 0x6000, v194
	v_addc_co_u32_e32 v195, vcc, 0, v195, vcc
	global_load_dword v176, v[194:195], off
	v_add_co_u32_e32 v194, vcc, 0x6000, v194
	v_addc_co_u32_e32 v195, vcc, 0, v195, vcc
	global_load_dword v177, v[194:195], off
	v_add_co_u32_e32 v194, vcc, 0x6000, v194
	v_addc_co_u32_e32 v195, vcc, 0, v195, vcc
	global_load_dword v178, v[194:195], off
	v_add_co_u32_e32 v194, vcc, 0x6000, v194
	v_addc_co_u32_e32 v195, vcc, 0, v195, vcc
	global_load_dword v179, v[194:195], off
	v_add_co_u32_e32 v194, vcc, 0x6000, v194
	v_addc_co_u32_e32 v195, vcc, 0, v195, vcc
	global_load_dword v180, v[194:195], off
	v_add_co_u32_e32 v194, vcc, 0x6000, v194
	v_addc_co_u32_e32 v195, vcc, 0, v195, vcc
	global_load_dword v181, v[194:195], off
	v_add_co_u32_e32 v194, vcc, 0x6000, v194
	v_addc_co_u32_e32 v195, vcc, 0, v195, vcc
	global_load_dword v182, v[194:195], off
	v_add_co_u32_e32 v194, vcc, 0x6000, v194
	v_addc_co_u32_e32 v195, vcc, 0, v195, vcc
	global_load_dword v183, v[194:195], off
	v_add_co_u32_e32 v194, vcc, 0x6000, v194
	v_addc_co_u32_e32 v195, vcc, 0, v195, vcc
	global_load_dword v184, v[194:195], off
	v_add_co_u32_e32 v194, vcc, 0x6000, v194
	v_addc_co_u32_e32 v195, vcc, 0, v195, vcc
	global_load_dword v185, v[194:195], off
	v_add_co_u32_e32 v194, vcc, 0x6000, v194
	v_addc_co_u32_e32 v195, vcc, 0, v195, vcc
	global_load_dword v186, v[194:195], off
	v_add_co_u32_e32 v194, vcc, 0x6000, v194
	v_addc_co_u32_e32 v195, vcc, 0, v195, vcc
	global_load_dword v187, v[194:195], off
	v_add_co_u32_e32 v194, vcc, 0x6000, v194
	v_addc_co_u32_e32 v195, vcc, 0, v195, vcc
	global_load_dword v188, v[194:195], off
	v_add_co_u32_e32 v194, vcc, 0x6000, v194
	v_addc_co_u32_e32 v195, vcc, 0, v195, vcc
	global_load_dword v189, v[194:195], off
	v_add_co_u32_e32 v194, vcc, 0x6000, v194
	v_addc_co_u32_e32 v195, vcc, 0, v195, vcc
	global_load_dword v190, v[194:195], off
	v_add_co_u32_e32 v194, vcc, 0x6000, v194
	v_addc_co_u32_e32 v195, vcc, 0, v195, vcc
	global_load_dword v191, v[194:195], off
	v_add_co_u32_e32 v194, vcc, 0x6000, v194
	v_addc_co_u32_e32 v195, vcc, 0, v195, vcc
	global_load_dword v192, v[194:195], off
	v_add_co_u32_e32 v194, vcc, 0x6000, v194
	v_addc_co_u32_e32 v195, vcc, 0, v195, vcc
	global_load_dword v193, v[194:195], off
	v_add_co_u32_e32 v194, vcc, 0x6000, v194
	v_addc_co_u32_e32 v195, vcc, 0, v195, vcc
	ds_read_b128 v[98:101], v8 offset:4096
	ds_read_b128 v[102:105], v8 offset:8192
	ds_read_b128 v[106:109], v8 offset:12288
	ds_read_b128 v[110:113], v8 offset:16384
	ds_read_b128 v[114:117], v8 offset:20480
	ds_read_b128 v[118:121], v8 offset:24576
	ds_read_b128 v[122:125], v8 offset:28672
	ds_read_b128 v[126:129], v8
	ds_read_b128 v[134:137], v8 offset:32768
	v_add_u32_e32 v8, 16, v8
	s_waitcnt vmcnt(40) lgkmcnt(0)
	v_pk_fma_f32 v[196:197], v[150:151], v[126:127], v[196:197]
	v_pk_fma_f32 v[198:199], v[150:151], v[98:99], v[198:199]
	v_pk_fma_f32 v[200:201], v[150:151], v[102:103], v[200:201]
	v_pk_fma_f32 v[202:203], v[150:151], v[106:107], v[202:203]
	v_pk_fma_f32 v[204:205], v[150:151], v[110:111], v[204:205]
	v_pk_fma_f32 v[206:207], v[150:151], v[114:115], v[206:207]
	v_pk_fma_f32 v[208:209], v[150:151], v[118:119], v[208:209]
	v_pk_fma_f32 v[210:211], v[150:151], v[122:123], v[210:211]
	v_pk_fma_f32 v[212:213], v[150:151], v[134:135], v[212:213]
	v_pk_fma_f32 v[196:197], v[152:153], v[128:129], v[196:197]
	v_pk_fma_f32 v[198:199], v[152:153], v[100:101], v[198:199]
	v_pk_fma_f32 v[200:201], v[152:153], v[104:105], v[200:201]
	v_pk_fma_f32 v[202:203], v[152:153], v[108:109], v[202:203]
	v_pk_fma_f32 v[204:205], v[152:153], v[112:113], v[204:205]
	v_pk_fma_f32 v[206:207], v[152:153], v[116:117], v[206:207]
	v_pk_fma_f32 v[208:209], v[152:153], v[120:121], v[208:209]
	v_pk_fma_f32 v[210:211], v[152:153], v[124:125], v[210:211]
	v_pk_fma_f32 v[212:213], v[152:153], v[136:137], v[212:213]
	global_load_dword v150, v[194:195], off
	v_add_co_u32_e32 v194, vcc, 0x6000, v194
	v_addc_co_u32_e32 v195, vcc, 0, v195, vcc
	global_load_dword v151, v[194:195], off
	v_add_co_u32_e32 v194, vcc, 0x6000, v194
	v_addc_co_u32_e32 v195, vcc, 0, v195, vcc
	global_load_dword v152, v[194:195], off
	v_add_co_u32_e32 v194, vcc, 0x6000, v194
	v_addc_co_u32_e32 v195, vcc, 0, v195, vcc
	global_load_dword v153, v[194:195], off
	v_add_co_u32_e32 v194, vcc, 0x6000, v194
	v_addc_co_u32_e32 v195, vcc, 0, v195, vcc
	ds_read_b128 v[98:101], v8 offset:4096
	ds_read_b128 v[102:105], v8 offset:8192
	ds_read_b128 v[106:109], v8 offset:12288
	ds_read_b128 v[110:113], v8 offset:16384
	ds_read_b128 v[114:117], v8 offset:20480
	ds_read_b128 v[118:121], v8 offset:24576
	ds_read_b128 v[122:125], v8 offset:28672
	ds_read_b128 v[126:129], v8
	ds_read_b128 v[134:137], v8 offset:32768
	v_add_u32_e32 v8, 16, v8
	s_waitcnt vmcnt(40) lgkmcnt(0)
	v_pk_fma_f32 v[196:197], v[154:155], v[126:127], v[196:197]
	v_pk_fma_f32 v[198:199], v[154:155], v[98:99], v[198:199]
	v_pk_fma_f32 v[200:201], v[154:155], v[102:103], v[200:201]
	v_pk_fma_f32 v[202:203], v[154:155], v[106:107], v[202:203]
	v_pk_fma_f32 v[204:205], v[154:155], v[110:111], v[204:205]
	v_pk_fma_f32 v[206:207], v[154:155], v[114:115], v[206:207]
	v_pk_fma_f32 v[208:209], v[154:155], v[118:119], v[208:209]
	v_pk_fma_f32 v[210:211], v[154:155], v[122:123], v[210:211]
	v_pk_fma_f32 v[212:213], v[154:155], v[134:135], v[212:213]
	v_pk_fma_f32 v[196:197], v[156:157], v[128:129], v[196:197]
	v_pk_fma_f32 v[198:199], v[156:157], v[100:101], v[198:199]
	v_pk_fma_f32 v[200:201], v[156:157], v[104:105], v[200:201]
	v_pk_fma_f32 v[202:203], v[156:157], v[108:109], v[202:203]
	v_pk_fma_f32 v[204:205], v[156:157], v[112:113], v[204:205]
	v_pk_fma_f32 v[206:207], v[156:157], v[116:117], v[206:207]
	v_pk_fma_f32 v[208:209], v[156:157], v[120:121], v[208:209]
	v_pk_fma_f32 v[210:211], v[156:157], v[124:125], v[210:211]
	v_pk_fma_f32 v[212:213], v[156:157], v[136:137], v[212:213]
	global_load_dword v154, v[194:195], off
	v_add_co_u32_e32 v194, vcc, 0x6000, v194
	v_addc_co_u32_e32 v195, vcc, 0, v195, vcc
	global_load_dword v155, v[194:195], off
	v_add_co_u32_e32 v194, vcc, 0x6000, v194
	v_addc_co_u32_e32 v195, vcc, 0, v195, vcc
	global_load_dword v156, v[194:195], off
	v_add_co_u32_e32 v194, vcc, 0x6000, v194
	v_addc_co_u32_e32 v195, vcc, 0, v195, vcc
	global_load_dword v157, v[194:195], off
	v_add_co_u32_e32 v194, vcc, 0x6000, v194
	v_addc_co_u32_e32 v195, vcc, 0, v195, vcc
	ds_read_b128 v[98:101], v8 offset:4096
	ds_read_b128 v[102:105], v8 offset:8192
	ds_read_b128 v[106:109], v8 offset:12288
	ds_read_b128 v[110:113], v8 offset:16384
	ds_read_b128 v[114:117], v8 offset:20480
	ds_read_b128 v[118:121], v8 offset:24576
	ds_read_b128 v[122:125], v8 offset:28672
	ds_read_b128 v[126:129], v8
	ds_read_b128 v[134:137], v8 offset:32768
	v_add_u32_e32 v8, 16, v8
	s_waitcnt vmcnt(40) lgkmcnt(0)
	v_pk_fma_f32 v[196:197], v[158:159], v[126:127], v[196:197]
	v_pk_fma_f32 v[198:199], v[158:159], v[98:99], v[198:199]
	v_pk_fma_f32 v[200:201], v[158:159], v[102:103], v[200:201]
	v_pk_fma_f32 v[202:203], v[158:159], v[106:107], v[202:203]
	v_pk_fma_f32 v[204:205], v[158:159], v[110:111], v[204:205]
	v_pk_fma_f32 v[206:207], v[158:159], v[114:115], v[206:207]
	v_pk_fma_f32 v[208:209], v[158:159], v[118:119], v[208:209]
	v_pk_fma_f32 v[210:211], v[158:159], v[122:123], v[210:211]
	v_pk_fma_f32 v[212:213], v[158:159], v[134:135], v[212:213]
	v_pk_fma_f32 v[196:197], v[160:161], v[128:129], v[196:197]
	v_pk_fma_f32 v[198:199], v[160:161], v[100:101], v[198:199]
	v_pk_fma_f32 v[200:201], v[160:161], v[104:105], v[200:201]
	v_pk_fma_f32 v[202:203], v[160:161], v[108:109], v[202:203]
	v_pk_fma_f32 v[204:205], v[160:161], v[112:113], v[204:205]
	v_pk_fma_f32 v[206:207], v[160:161], v[116:117], v[206:207]
	v_pk_fma_f32 v[208:209], v[160:161], v[120:121], v[208:209]
	v_pk_fma_f32 v[210:211], v[160:161], v[124:125], v[210:211]
	v_pk_fma_f32 v[212:213], v[160:161], v[136:137], v[212:213]
	global_load_dword v158, v[194:195], off
	v_add_co_u32_e32 v194, vcc, 0x6000, v194
	v_addc_co_u32_e32 v195, vcc, 0, v195, vcc
	global_load_dword v159, v[194:195], off
	v_add_co_u32_e32 v194, vcc, 0x6000, v194
	v_addc_co_u32_e32 v195, vcc, 0, v195, vcc
	global_load_dword v160, v[194:195], off
	v_add_co_u32_e32 v194, vcc, 0x6000, v194
	v_addc_co_u32_e32 v195, vcc, 0, v195, vcc
	global_load_dword v161, v[194:195], off
	v_add_co_u32_e32 v194, vcc, 0x6000, v194
	v_addc_co_u32_e32 v195, vcc, 0, v195, vcc
	ds_read_b128 v[98:101], v8 offset:4096
	ds_read_b128 v[102:105], v8 offset:8192
	ds_read_b128 v[106:109], v8 offset:12288
	ds_read_b128 v[110:113], v8 offset:16384
	ds_read_b128 v[114:117], v8 offset:20480
	ds_read_b128 v[118:121], v8 offset:24576
	ds_read_b128 v[122:125], v8 offset:28672
	ds_read_b128 v[126:129], v8
	ds_read_b128 v[134:137], v8 offset:32768
	v_add_u32_e32 v8, 16, v8
	s_waitcnt vmcnt(40) lgkmcnt(0)
	v_pk_fma_f32 v[196:197], v[162:163], v[126:127], v[196:197]
	v_pk_fma_f32 v[198:199], v[162:163], v[98:99], v[198:199]
	v_pk_fma_f32 v[200:201], v[162:163], v[102:103], v[200:201]
	v_pk_fma_f32 v[202:203], v[162:163], v[106:107], v[202:203]
	v_pk_fma_f32 v[204:205], v[162:163], v[110:111], v[204:205]
	v_pk_fma_f32 v[206:207], v[162:163], v[114:115], v[206:207]
	v_pk_fma_f32 v[208:209], v[162:163], v[118:119], v[208:209]
	v_pk_fma_f32 v[210:211], v[162:163], v[122:123], v[210:211]
	v_pk_fma_f32 v[212:213], v[162:163], v[134:135], v[212:213]
	v_pk_fma_f32 v[196:197], v[164:165], v[128:129], v[196:197]
	v_pk_fma_f32 v[198:199], v[164:165], v[100:101], v[198:199]
	v_pk_fma_f32 v[200:201], v[164:165], v[104:105], v[200:201]
	v_pk_fma_f32 v[202:203], v[164:165], v[108:109], v[202:203]
	v_pk_fma_f32 v[204:205], v[164:165], v[112:113], v[204:205]
	v_pk_fma_f32 v[206:207], v[164:165], v[116:117], v[206:207]
	v_pk_fma_f32 v[208:209], v[164:165], v[120:121], v[208:209]
	v_pk_fma_f32 v[210:211], v[164:165], v[124:125], v[210:211]
	v_pk_fma_f32 v[212:213], v[164:165], v[136:137], v[212:213]
	global_load_dword v162, v[194:195], off
	v_add_co_u32_e32 v194, vcc, 0x6000, v194
	v_addc_co_u32_e32 v195, vcc, 0, v195, vcc
	global_load_dword v163, v[194:195], off
	v_add_co_u32_e32 v194, vcc, 0x6000, v194
	v_addc_co_u32_e32 v195, vcc, 0, v195, vcc
	global_load_dword v164, v[194:195], off
	v_add_co_u32_e32 v194, vcc, 0x6000, v194
	v_addc_co_u32_e32 v195, vcc, 0, v195, vcc
	global_load_dword v165, v[194:195], off
	v_add_co_u32_e32 v194, vcc, 0x6000, v194
	v_addc_co_u32_e32 v195, vcc, 0, v195, vcc
	ds_read_b128 v[98:101], v8 offset:4096
	ds_read_b128 v[102:105], v8 offset:8192
	ds_read_b128 v[106:109], v8 offset:12288
	ds_read_b128 v[110:113], v8 offset:16384
	ds_read_b128 v[114:117], v8 offset:20480
	ds_read_b128 v[118:121], v8 offset:24576
	ds_read_b128 v[122:125], v8 offset:28672
	ds_read_b128 v[126:129], v8
	ds_read_b128 v[134:137], v8 offset:32768
	v_add_u32_e32 v8, 16, v8
	s_waitcnt vmcnt(40) lgkmcnt(0)
	v_pk_fma_f32 v[196:197], v[166:167], v[126:127], v[196:197]
	v_pk_fma_f32 v[198:199], v[166:167], v[98:99], v[198:199]
	v_pk_fma_f32 v[200:201], v[166:167], v[102:103], v[200:201]
	v_pk_fma_f32 v[202:203], v[166:167], v[106:107], v[202:203]
	v_pk_fma_f32 v[204:205], v[166:167], v[110:111], v[204:205]
	v_pk_fma_f32 v[206:207], v[166:167], v[114:115], v[206:207]
	v_pk_fma_f32 v[208:209], v[166:167], v[118:119], v[208:209]
	v_pk_fma_f32 v[210:211], v[166:167], v[122:123], v[210:211]
	v_pk_fma_f32 v[212:213], v[166:167], v[134:135], v[212:213]
	v_pk_fma_f32 v[196:197], v[168:169], v[128:129], v[196:197]
	v_pk_fma_f32 v[198:199], v[168:169], v[100:101], v[198:199]
	v_pk_fma_f32 v[200:201], v[168:169], v[104:105], v[200:201]
	v_pk_fma_f32 v[202:203], v[168:169], v[108:109], v[202:203]
	v_pk_fma_f32 v[204:205], v[168:169], v[112:113], v[204:205]
	v_pk_fma_f32 v[206:207], v[168:169], v[116:117], v[206:207]
	v_pk_fma_f32 v[208:209], v[168:169], v[120:121], v[208:209]
	v_pk_fma_f32 v[210:211], v[168:169], v[124:125], v[210:211]
	v_pk_fma_f32 v[212:213], v[168:169], v[136:137], v[212:213]
	global_load_dword v166, v[194:195], off
	v_add_co_u32_e32 v194, vcc, 0x6000, v194
	v_addc_co_u32_e32 v195, vcc, 0, v195, vcc
	global_load_dword v167, v[194:195], off
	v_add_co_u32_e32 v194, vcc, 0x6000, v194
	v_addc_co_u32_e32 v195, vcc, 0, v195, vcc
	global_load_dword v168, v[194:195], off
	v_add_co_u32_e32 v194, vcc, 0x6000, v194
	v_addc_co_u32_e32 v195, vcc, 0, v195, vcc
	global_load_dword v169, v[194:195], off
	v_add_co_u32_e32 v194, vcc, 0x6000, v194
	v_addc_co_u32_e32 v195, vcc, 0, v195, vcc
	ds_read_b128 v[98:101], v8 offset:4096
	ds_read_b128 v[102:105], v8 offset:8192
	ds_read_b128 v[106:109], v8 offset:12288
	ds_read_b128 v[110:113], v8 offset:16384
	ds_read_b128 v[114:117], v8 offset:20480
	ds_read_b128 v[118:121], v8 offset:24576
	ds_read_b128 v[122:125], v8 offset:28672
	ds_read_b128 v[126:129], v8
	ds_read_b128 v[134:137], v8 offset:32768
	v_add_u32_e32 v8, 16, v8
	s_waitcnt vmcnt(40) lgkmcnt(0)
	v_pk_fma_f32 v[196:197], v[170:171], v[126:127], v[196:197]
	v_pk_fma_f32 v[198:199], v[170:171], v[98:99], v[198:199]
	v_pk_fma_f32 v[200:201], v[170:171], v[102:103], v[200:201]
	v_pk_fma_f32 v[202:203], v[170:171], v[106:107], v[202:203]
	v_pk_fma_f32 v[204:205], v[170:171], v[110:111], v[204:205]
	v_pk_fma_f32 v[206:207], v[170:171], v[114:115], v[206:207]
	v_pk_fma_f32 v[208:209], v[170:171], v[118:119], v[208:209]
	v_pk_fma_f32 v[210:211], v[170:171], v[122:123], v[210:211]
	v_pk_fma_f32 v[212:213], v[170:171], v[134:135], v[212:213]
	v_pk_fma_f32 v[196:197], v[172:173], v[128:129], v[196:197]
	v_pk_fma_f32 v[198:199], v[172:173], v[100:101], v[198:199]
	v_pk_fma_f32 v[200:201], v[172:173], v[104:105], v[200:201]
	v_pk_fma_f32 v[202:203], v[172:173], v[108:109], v[202:203]
	v_pk_fma_f32 v[204:205], v[172:173], v[112:113], v[204:205]
	v_pk_fma_f32 v[206:207], v[172:173], v[116:117], v[206:207]
	v_pk_fma_f32 v[208:209], v[172:173], v[120:121], v[208:209]
	v_pk_fma_f32 v[210:211], v[172:173], v[124:125], v[210:211]
	v_pk_fma_f32 v[212:213], v[172:173], v[136:137], v[212:213]
	global_load_dword v170, v[194:195], off
	v_add_co_u32_e32 v194, vcc, 0x6000, v194
	v_addc_co_u32_e32 v195, vcc, 0, v195, vcc
	global_load_dword v171, v[194:195], off
	v_add_co_u32_e32 v194, vcc, 0x6000, v194
	v_addc_co_u32_e32 v195, vcc, 0, v195, vcc
	global_load_dword v172, v[194:195], off
	v_add_co_u32_e32 v194, vcc, 0x6000, v194
	v_addc_co_u32_e32 v195, vcc, 0, v195, vcc
	global_load_dword v173, v[194:195], off
	v_add_co_u32_e32 v194, vcc, 0x6000, v194
	v_addc_co_u32_e32 v195, vcc, 0, v195, vcc
	ds_read_b128 v[98:101], v8 offset:4096
	ds_read_b128 v[102:105], v8 offset:8192
	ds_read_b128 v[106:109], v8 offset:12288
	ds_read_b128 v[110:113], v8 offset:16384
	ds_read_b128 v[114:117], v8 offset:20480
	ds_read_b128 v[118:121], v8 offset:24576
	ds_read_b128 v[122:125], v8 offset:28672
	ds_read_b128 v[126:129], v8
	ds_read_b128 v[134:137], v8 offset:32768
	v_add_u32_e32 v8, 16, v8
	s_waitcnt vmcnt(40) lgkmcnt(0)
	v_pk_fma_f32 v[196:197], v[174:175], v[126:127], v[196:197]
	v_pk_fma_f32 v[198:199], v[174:175], v[98:99], v[198:199]
	v_pk_fma_f32 v[200:201], v[174:175], v[102:103], v[200:201]
	v_pk_fma_f32 v[202:203], v[174:175], v[106:107], v[202:203]
	v_pk_fma_f32 v[204:205], v[174:175], v[110:111], v[204:205]
	v_pk_fma_f32 v[206:207], v[174:175], v[114:115], v[206:207]
	v_pk_fma_f32 v[208:209], v[174:175], v[118:119], v[208:209]
	v_pk_fma_f32 v[210:211], v[174:175], v[122:123], v[210:211]
	v_pk_fma_f32 v[212:213], v[174:175], v[134:135], v[212:213]
	v_pk_fma_f32 v[196:197], v[176:177], v[128:129], v[196:197]
	v_pk_fma_f32 v[198:199], v[176:177], v[100:101], v[198:199]
	v_pk_fma_f32 v[200:201], v[176:177], v[104:105], v[200:201]
	v_pk_fma_f32 v[202:203], v[176:177], v[108:109], v[202:203]
	v_pk_fma_f32 v[204:205], v[176:177], v[112:113], v[204:205]
	v_pk_fma_f32 v[206:207], v[176:177], v[116:117], v[206:207]
	v_pk_fma_f32 v[208:209], v[176:177], v[120:121], v[208:209]
	v_pk_fma_f32 v[210:211], v[176:177], v[124:125], v[210:211]
	v_pk_fma_f32 v[212:213], v[176:177], v[136:137], v[212:213]
	global_load_dword v174, v[194:195], off
	v_add_co_u32_e32 v194, vcc, 0x6000, v194
	v_addc_co_u32_e32 v195, vcc, 0, v195, vcc
	global_load_dword v175, v[194:195], off
	v_add_co_u32_e32 v194, vcc, 0x6000, v194
	v_addc_co_u32_e32 v195, vcc, 0, v195, vcc
	global_load_dword v176, v[194:195], off
	v_add_co_u32_e32 v194, vcc, 0x6000, v194
	v_addc_co_u32_e32 v195, vcc, 0, v195, vcc
	global_load_dword v177, v[194:195], off
	v_add_co_u32_e32 v194, vcc, 0x6000, v194
	v_addc_co_u32_e32 v195, vcc, 0, v195, vcc
	ds_read_b128 v[98:101], v8 offset:4096
	ds_read_b128 v[102:105], v8 offset:8192
	ds_read_b128 v[106:109], v8 offset:12288
	ds_read_b128 v[110:113], v8 offset:16384
	ds_read_b128 v[114:117], v8 offset:20480
	ds_read_b128 v[118:121], v8 offset:24576
	ds_read_b128 v[122:125], v8 offset:28672
	ds_read_b128 v[126:129], v8
	ds_read_b128 v[134:137], v8 offset:32768
	v_add_u32_e32 v8, 16, v8
	s_waitcnt vmcnt(40) lgkmcnt(0)
	v_pk_fma_f32 v[196:197], v[178:179], v[126:127], v[196:197]
	v_pk_fma_f32 v[198:199], v[178:179], v[98:99], v[198:199]
	v_pk_fma_f32 v[200:201], v[178:179], v[102:103], v[200:201]
	v_pk_fma_f32 v[202:203], v[178:179], v[106:107], v[202:203]
	v_pk_fma_f32 v[204:205], v[178:179], v[110:111], v[204:205]
	v_pk_fma_f32 v[206:207], v[178:179], v[114:115], v[206:207]
	v_pk_fma_f32 v[208:209], v[178:179], v[118:119], v[208:209]
	v_pk_fma_f32 v[210:211], v[178:179], v[122:123], v[210:211]
	v_pk_fma_f32 v[212:213], v[178:179], v[134:135], v[212:213]
	v_pk_fma_f32 v[196:197], v[180:181], v[128:129], v[196:197]
	v_pk_fma_f32 v[198:199], v[180:181], v[100:101], v[198:199]
	v_pk_fma_f32 v[200:201], v[180:181], v[104:105], v[200:201]
	v_pk_fma_f32 v[202:203], v[180:181], v[108:109], v[202:203]
	v_pk_fma_f32 v[204:205], v[180:181], v[112:113], v[204:205]
	v_pk_fma_f32 v[206:207], v[180:181], v[116:117], v[206:207]
	v_pk_fma_f32 v[208:209], v[180:181], v[120:121], v[208:209]
	v_pk_fma_f32 v[210:211], v[180:181], v[124:125], v[210:211]
	v_pk_fma_f32 v[212:213], v[180:181], v[136:137], v[212:213]
	global_load_dword v178, v[194:195], off
	v_add_co_u32_e32 v194, vcc, 0x6000, v194
	v_addc_co_u32_e32 v195, vcc, 0, v195, vcc
	global_load_dword v179, v[194:195], off
	v_add_co_u32_e32 v194, vcc, 0x6000, v194
	v_addc_co_u32_e32 v195, vcc, 0, v195, vcc
	global_load_dword v180, v[194:195], off
	v_add_co_u32_e32 v194, vcc, 0x6000, v194
	v_addc_co_u32_e32 v195, vcc, 0, v195, vcc
	global_load_dword v181, v[194:195], off
	v_add_co_u32_e32 v194, vcc, 0x6000, v194
	v_addc_co_u32_e32 v195, vcc, 0, v195, vcc
	ds_read_b128 v[98:101], v8 offset:4096
	ds_read_b128 v[102:105], v8 offset:8192
	ds_read_b128 v[106:109], v8 offset:12288
	ds_read_b128 v[110:113], v8 offset:16384
	ds_read_b128 v[114:117], v8 offset:20480
	ds_read_b128 v[118:121], v8 offset:24576
	ds_read_b128 v[122:125], v8 offset:28672
	ds_read_b128 v[126:129], v8
	ds_read_b128 v[134:137], v8 offset:32768
	v_add_u32_e32 v8, 16, v8
	s_waitcnt vmcnt(40) lgkmcnt(0)
	v_pk_fma_f32 v[196:197], v[182:183], v[126:127], v[196:197]
	v_pk_fma_f32 v[198:199], v[182:183], v[98:99], v[198:199]
	v_pk_fma_f32 v[200:201], v[182:183], v[102:103], v[200:201]
	v_pk_fma_f32 v[202:203], v[182:183], v[106:107], v[202:203]
	v_pk_fma_f32 v[204:205], v[182:183], v[110:111], v[204:205]
	v_pk_fma_f32 v[206:207], v[182:183], v[114:115], v[206:207]
	v_pk_fma_f32 v[208:209], v[182:183], v[118:119], v[208:209]
	v_pk_fma_f32 v[210:211], v[182:183], v[122:123], v[210:211]
	v_pk_fma_f32 v[212:213], v[182:183], v[134:135], v[212:213]
	v_pk_fma_f32 v[196:197], v[184:185], v[128:129], v[196:197]
	v_pk_fma_f32 v[198:199], v[184:185], v[100:101], v[198:199]
	v_pk_fma_f32 v[200:201], v[184:185], v[104:105], v[200:201]
	v_pk_fma_f32 v[202:203], v[184:185], v[108:109], v[202:203]
	v_pk_fma_f32 v[204:205], v[184:185], v[112:113], v[204:205]
	v_pk_fma_f32 v[206:207], v[184:185], v[116:117], v[206:207]
	v_pk_fma_f32 v[208:209], v[184:185], v[120:121], v[208:209]
	v_pk_fma_f32 v[210:211], v[184:185], v[124:125], v[210:211]
	v_pk_fma_f32 v[212:213], v[184:185], v[136:137], v[212:213]
	global_load_dword v182, v[194:195], off
	v_add_co_u32_e32 v194, vcc, 0x6000, v194
	v_addc_co_u32_e32 v195, vcc, 0, v195, vcc
	global_load_dword v183, v[194:195], off
	v_add_co_u32_e32 v194, vcc, 0x6000, v194
	v_addc_co_u32_e32 v195, vcc, 0, v195, vcc
	global_load_dword v184, v[194:195], off
	v_add_co_u32_e32 v194, vcc, 0x6000, v194
	v_addc_co_u32_e32 v195, vcc, 0, v195, vcc
	global_load_dword v185, v[194:195], off
	v_add_co_u32_e32 v194, vcc, 0x6000, v194
	v_addc_co_u32_e32 v195, vcc, 0, v195, vcc
	ds_read_b128 v[98:101], v8 offset:4096
	ds_read_b128 v[102:105], v8 offset:8192
	ds_read_b128 v[106:109], v8 offset:12288
	ds_read_b128 v[110:113], v8 offset:16384
	ds_read_b128 v[114:117], v8 offset:20480
	ds_read_b128 v[118:121], v8 offset:24576
	ds_read_b128 v[122:125], v8 offset:28672
	ds_read_b128 v[126:129], v8
	ds_read_b128 v[134:137], v8 offset:32768
	v_add_u32_e32 v8, 16, v8
	s_waitcnt vmcnt(40) lgkmcnt(0)
	v_pk_fma_f32 v[196:197], v[186:187], v[126:127], v[196:197]
	v_pk_fma_f32 v[198:199], v[186:187], v[98:99], v[198:199]
	v_pk_fma_f32 v[200:201], v[186:187], v[102:103], v[200:201]
	v_pk_fma_f32 v[202:203], v[186:187], v[106:107], v[202:203]
	v_pk_fma_f32 v[204:205], v[186:187], v[110:111], v[204:205]
	v_pk_fma_f32 v[206:207], v[186:187], v[114:115], v[206:207]
	v_pk_fma_f32 v[208:209], v[186:187], v[118:119], v[208:209]
	v_pk_fma_f32 v[210:211], v[186:187], v[122:123], v[210:211]
	v_pk_fma_f32 v[212:213], v[186:187], v[134:135], v[212:213]
	v_pk_fma_f32 v[196:197], v[188:189], v[128:129], v[196:197]
	v_pk_fma_f32 v[198:199], v[188:189], v[100:101], v[198:199]
	v_pk_fma_f32 v[200:201], v[188:189], v[104:105], v[200:201]
	v_pk_fma_f32 v[202:203], v[188:189], v[108:109], v[202:203]
	v_pk_fma_f32 v[204:205], v[188:189], v[112:113], v[204:205]
	v_pk_fma_f32 v[206:207], v[188:189], v[116:117], v[206:207]
	v_pk_fma_f32 v[208:209], v[188:189], v[120:121], v[208:209]
	v_pk_fma_f32 v[210:211], v[188:189], v[124:125], v[210:211]
	v_pk_fma_f32 v[212:213], v[188:189], v[136:137], v[212:213]
	global_load_dword v186, v[194:195], off
	v_add_co_u32_e32 v194, vcc, 0x6000, v194
	v_addc_co_u32_e32 v195, vcc, 0, v195, vcc
	global_load_dword v187, v[194:195], off
	v_add_co_u32_e32 v194, vcc, 0x6000, v194
	v_addc_co_u32_e32 v195, vcc, 0, v195, vcc
	global_load_dword v188, v[194:195], off
	v_add_co_u32_e32 v194, vcc, 0x6000, v194
	v_addc_co_u32_e32 v195, vcc, 0, v195, vcc
	global_load_dword v189, v[194:195], off
	v_add_co_u32_e32 v194, vcc, 0x6000, v194
	v_addc_co_u32_e32 v195, vcc, 0, v195, vcc
	ds_read_b128 v[98:101], v8 offset:4096
	ds_read_b128 v[102:105], v8 offset:8192
	ds_read_b128 v[106:109], v8 offset:12288
	ds_read_b128 v[110:113], v8 offset:16384
	ds_read_b128 v[114:117], v8 offset:20480
	ds_read_b128 v[118:121], v8 offset:24576
	ds_read_b128 v[122:125], v8 offset:28672
	ds_read_b128 v[126:129], v8
	ds_read_b128 v[134:137], v8 offset:32768
	v_add_u32_e32 v8, 16, v8
	s_waitcnt vmcnt(40) lgkmcnt(0)
	v_pk_fma_f32 v[196:197], v[190:191], v[126:127], v[196:197]
	v_pk_fma_f32 v[198:199], v[190:191], v[98:99], v[198:199]
	v_pk_fma_f32 v[200:201], v[190:191], v[102:103], v[200:201]
	v_pk_fma_f32 v[202:203], v[190:191], v[106:107], v[202:203]
	v_pk_fma_f32 v[204:205], v[190:191], v[110:111], v[204:205]
	v_pk_fma_f32 v[206:207], v[190:191], v[114:115], v[206:207]
	v_pk_fma_f32 v[208:209], v[190:191], v[118:119], v[208:209]
	v_pk_fma_f32 v[210:211], v[190:191], v[122:123], v[210:211]
	v_pk_fma_f32 v[212:213], v[190:191], v[134:135], v[212:213]
	v_pk_fma_f32 v[196:197], v[192:193], v[128:129], v[196:197]
	v_pk_fma_f32 v[198:199], v[192:193], v[100:101], v[198:199]
	v_pk_fma_f32 v[200:201], v[192:193], v[104:105], v[200:201]
	v_pk_fma_f32 v[202:203], v[192:193], v[108:109], v[202:203]
	v_pk_fma_f32 v[204:205], v[192:193], v[112:113], v[204:205]
	v_pk_fma_f32 v[206:207], v[192:193], v[116:117], v[206:207]
	v_pk_fma_f32 v[208:209], v[192:193], v[120:121], v[208:209]
	v_pk_fma_f32 v[210:211], v[192:193], v[124:125], v[210:211]
	v_pk_fma_f32 v[212:213], v[192:193], v[136:137], v[212:213]
	global_load_dword v190, v[194:195], off
	v_add_co_u32_e32 v194, vcc, 0x6000, v194
	v_addc_co_u32_e32 v195, vcc, 0, v195, vcc
	global_load_dword v191, v[194:195], off
	v_add_co_u32_e32 v194, vcc, 0x6000, v194
	v_addc_co_u32_e32 v195, vcc, 0, v195, vcc
	global_load_dword v192, v[194:195], off
	v_add_co_u32_e32 v194, vcc, 0x6000, v194
	v_addc_co_u32_e32 v195, vcc, 0, v195, vcc
	global_load_dword v193, v[194:195], off
	v_add_co_u32_e32 v194, vcc, 0x6000, v194
	v_addc_co_u32_e32 v195, vcc, 0, v195, vcc
	ds_read_b128 v[98:101], v8 offset:4096
	ds_read_b128 v[102:105], v8 offset:8192
	ds_read_b128 v[106:109], v8 offset:12288
	ds_read_b128 v[110:113], v8 offset:16384
	ds_read_b128 v[114:117], v8 offset:20480
	ds_read_b128 v[118:121], v8 offset:24576
	ds_read_b128 v[122:125], v8 offset:28672
	ds_read_b128 v[126:129], v8
	ds_read_b128 v[134:137], v8 offset:32768
	v_add_u32_e32 v8, 16, v8
	s_waitcnt vmcnt(40) lgkmcnt(0)
	v_pk_fma_f32 v[196:197], v[150:151], v[126:127], v[196:197]
	v_pk_fma_f32 v[198:199], v[150:151], v[98:99], v[198:199]
	v_pk_fma_f32 v[200:201], v[150:151], v[102:103], v[200:201]
	v_pk_fma_f32 v[202:203], v[150:151], v[106:107], v[202:203]
	v_pk_fma_f32 v[204:205], v[150:151], v[110:111], v[204:205]
	v_pk_fma_f32 v[206:207], v[150:151], v[114:115], v[206:207]
	v_pk_fma_f32 v[208:209], v[150:151], v[118:119], v[208:209]
	v_pk_fma_f32 v[210:211], v[150:151], v[122:123], v[210:211]
	v_pk_fma_f32 v[212:213], v[150:151], v[134:135], v[212:213]
	v_pk_fma_f32 v[196:197], v[152:153], v[128:129], v[196:197]
	v_pk_fma_f32 v[198:199], v[152:153], v[100:101], v[198:199]
	v_pk_fma_f32 v[200:201], v[152:153], v[104:105], v[200:201]
	v_pk_fma_f32 v[202:203], v[152:153], v[108:109], v[202:203]
	v_pk_fma_f32 v[204:205], v[152:153], v[112:113], v[204:205]
	v_pk_fma_f32 v[206:207], v[152:153], v[116:117], v[206:207]
	v_pk_fma_f32 v[208:209], v[152:153], v[120:121], v[208:209]
	v_pk_fma_f32 v[210:211], v[152:153], v[124:125], v[210:211]
	v_pk_fma_f32 v[212:213], v[152:153], v[136:137], v[212:213]
	global_load_dword v150, v[194:195], off
	v_add_co_u32_e32 v194, vcc, 0x6000, v194
	v_addc_co_u32_e32 v195, vcc, 0, v195, vcc
	global_load_dword v151, v[194:195], off
	v_add_co_u32_e32 v194, vcc, 0x6000, v194
	v_addc_co_u32_e32 v195, vcc, 0, v195, vcc
	global_load_dword v152, v[194:195], off
	v_add_co_u32_e32 v194, vcc, 0x6000, v194
	v_addc_co_u32_e32 v195, vcc, 0, v195, vcc
	global_load_dword v153, v[194:195], off
	v_add_co_u32_e32 v194, vcc, 0x6000, v194
	v_addc_co_u32_e32 v195, vcc, 0, v195, vcc
	ds_read_b128 v[98:101], v8 offset:4096
	ds_read_b128 v[102:105], v8 offset:8192
	ds_read_b128 v[106:109], v8 offset:12288
	ds_read_b128 v[110:113], v8 offset:16384
	ds_read_b128 v[114:117], v8 offset:20480
	ds_read_b128 v[118:121], v8 offset:24576
	ds_read_b128 v[122:125], v8 offset:28672
	ds_read_b128 v[126:129], v8
	ds_read_b128 v[134:137], v8 offset:32768
	v_add_u32_e32 v8, 16, v8
	s_waitcnt vmcnt(40) lgkmcnt(0)
	v_pk_fma_f32 v[196:197], v[154:155], v[126:127], v[196:197]
	v_pk_fma_f32 v[198:199], v[154:155], v[98:99], v[198:199]
	v_pk_fma_f32 v[200:201], v[154:155], v[102:103], v[200:201]
	v_pk_fma_f32 v[202:203], v[154:155], v[106:107], v[202:203]
	v_pk_fma_f32 v[204:205], v[154:155], v[110:111], v[204:205]
	v_pk_fma_f32 v[206:207], v[154:155], v[114:115], v[206:207]
	v_pk_fma_f32 v[208:209], v[154:155], v[118:119], v[208:209]
	v_pk_fma_f32 v[210:211], v[154:155], v[122:123], v[210:211]
	v_pk_fma_f32 v[212:213], v[154:155], v[134:135], v[212:213]
	v_pk_fma_f32 v[196:197], v[156:157], v[128:129], v[196:197]
	v_pk_fma_f32 v[198:199], v[156:157], v[100:101], v[198:199]
	v_pk_fma_f32 v[200:201], v[156:157], v[104:105], v[200:201]
	v_pk_fma_f32 v[202:203], v[156:157], v[108:109], v[202:203]
	v_pk_fma_f32 v[204:205], v[156:157], v[112:113], v[204:205]
	v_pk_fma_f32 v[206:207], v[156:157], v[116:117], v[206:207]
	v_pk_fma_f32 v[208:209], v[156:157], v[120:121], v[208:209]
	v_pk_fma_f32 v[210:211], v[156:157], v[124:125], v[210:211]
	v_pk_fma_f32 v[212:213], v[156:157], v[136:137], v[212:213]
	global_load_dword v154, v[194:195], off
	v_add_co_u32_e32 v194, vcc, 0x6000, v194
	v_addc_co_u32_e32 v195, vcc, 0, v195, vcc
	global_load_dword v155, v[194:195], off
	v_add_co_u32_e32 v194, vcc, 0x6000, v194
	v_addc_co_u32_e32 v195, vcc, 0, v195, vcc
	global_load_dword v156, v[194:195], off
	v_add_co_u32_e32 v194, vcc, 0x6000, v194
	v_addc_co_u32_e32 v195, vcc, 0, v195, vcc
	global_load_dword v157, v[194:195], off
	v_add_co_u32_e32 v194, vcc, 0x6000, v194
	v_addc_co_u32_e32 v195, vcc, 0, v195, vcc
	ds_read_b128 v[98:101], v8 offset:4096
	ds_read_b128 v[102:105], v8 offset:8192
	ds_read_b128 v[106:109], v8 offset:12288
	ds_read_b128 v[110:113], v8 offset:16384
	ds_read_b128 v[114:117], v8 offset:20480
	ds_read_b128 v[118:121], v8 offset:24576
	ds_read_b128 v[122:125], v8 offset:28672
	ds_read_b128 v[126:129], v8
	ds_read_b128 v[134:137], v8 offset:32768
	v_add_u32_e32 v8, 16, v8
	s_waitcnt vmcnt(40) lgkmcnt(0)
	v_pk_fma_f32 v[196:197], v[158:159], v[126:127], v[196:197]
	v_pk_fma_f32 v[198:199], v[158:159], v[98:99], v[198:199]
	v_pk_fma_f32 v[200:201], v[158:159], v[102:103], v[200:201]
	v_pk_fma_f32 v[202:203], v[158:159], v[106:107], v[202:203]
	v_pk_fma_f32 v[204:205], v[158:159], v[110:111], v[204:205]
	v_pk_fma_f32 v[206:207], v[158:159], v[114:115], v[206:207]
	v_pk_fma_f32 v[208:209], v[158:159], v[118:119], v[208:209]
	v_pk_fma_f32 v[210:211], v[158:159], v[122:123], v[210:211]
	v_pk_fma_f32 v[212:213], v[158:159], v[134:135], v[212:213]
	v_pk_fma_f32 v[196:197], v[160:161], v[128:129], v[196:197]
	v_pk_fma_f32 v[198:199], v[160:161], v[100:101], v[198:199]
	v_pk_fma_f32 v[200:201], v[160:161], v[104:105], v[200:201]
	v_pk_fma_f32 v[202:203], v[160:161], v[108:109], v[202:203]
	v_pk_fma_f32 v[204:205], v[160:161], v[112:113], v[204:205]
	v_pk_fma_f32 v[206:207], v[160:161], v[116:117], v[206:207]
	v_pk_fma_f32 v[208:209], v[160:161], v[120:121], v[208:209]
	v_pk_fma_f32 v[210:211], v[160:161], v[124:125], v[210:211]
	v_pk_fma_f32 v[212:213], v[160:161], v[136:137], v[212:213]
	global_load_dword v158, v[194:195], off
	v_add_co_u32_e32 v194, vcc, 0x6000, v194
	v_addc_co_u32_e32 v195, vcc, 0, v195, vcc
	global_load_dword v159, v[194:195], off
	v_add_co_u32_e32 v194, vcc, 0x6000, v194
	v_addc_co_u32_e32 v195, vcc, 0, v195, vcc
	global_load_dword v160, v[194:195], off
	v_add_co_u32_e32 v194, vcc, 0x6000, v194
	v_addc_co_u32_e32 v195, vcc, 0, v195, vcc
	global_load_dword v161, v[194:195], off
	v_add_co_u32_e32 v194, vcc, 0x6000, v194
	v_addc_co_u32_e32 v195, vcc, 0, v195, vcc
	ds_read_b128 v[98:101], v8 offset:4096
	ds_read_b128 v[102:105], v8 offset:8192
	ds_read_b128 v[106:109], v8 offset:12288
	ds_read_b128 v[110:113], v8 offset:16384
	ds_read_b128 v[114:117], v8 offset:20480
	ds_read_b128 v[118:121], v8 offset:24576
	ds_read_b128 v[122:125], v8 offset:28672
	ds_read_b128 v[126:129], v8
	ds_read_b128 v[134:137], v8 offset:32768
	v_add_u32_e32 v8, 16, v8
	s_waitcnt vmcnt(40) lgkmcnt(0)
	v_pk_fma_f32 v[196:197], v[162:163], v[126:127], v[196:197]
	v_pk_fma_f32 v[198:199], v[162:163], v[98:99], v[198:199]
	v_pk_fma_f32 v[200:201], v[162:163], v[102:103], v[200:201]
	v_pk_fma_f32 v[202:203], v[162:163], v[106:107], v[202:203]
	v_pk_fma_f32 v[204:205], v[162:163], v[110:111], v[204:205]
	v_pk_fma_f32 v[206:207], v[162:163], v[114:115], v[206:207]
	v_pk_fma_f32 v[208:209], v[162:163], v[118:119], v[208:209]
	v_pk_fma_f32 v[210:211], v[162:163], v[122:123], v[210:211]
	v_pk_fma_f32 v[212:213], v[162:163], v[134:135], v[212:213]
	v_pk_fma_f32 v[196:197], v[164:165], v[128:129], v[196:197]
	v_pk_fma_f32 v[198:199], v[164:165], v[100:101], v[198:199]
	v_pk_fma_f32 v[200:201], v[164:165], v[104:105], v[200:201]
	v_pk_fma_f32 v[202:203], v[164:165], v[108:109], v[202:203]
	v_pk_fma_f32 v[204:205], v[164:165], v[112:113], v[204:205]
	v_pk_fma_f32 v[206:207], v[164:165], v[116:117], v[206:207]
	v_pk_fma_f32 v[208:209], v[164:165], v[120:121], v[208:209]
	v_pk_fma_f32 v[210:211], v[164:165], v[124:125], v[210:211]
	v_pk_fma_f32 v[212:213], v[164:165], v[136:137], v[212:213]
	global_load_dword v162, v[194:195], off
	v_add_co_u32_e32 v194, vcc, 0x6000, v194
	v_addc_co_u32_e32 v195, vcc, 0, v195, vcc
	global_load_dword v163, v[194:195], off
	v_add_co_u32_e32 v194, vcc, 0x6000, v194
	v_addc_co_u32_e32 v195, vcc, 0, v195, vcc
	global_load_dword v164, v[194:195], off
	v_add_co_u32_e32 v194, vcc, 0x6000, v194
	v_addc_co_u32_e32 v195, vcc, 0, v195, vcc
	global_load_dword v165, v[194:195], off
	v_add_co_u32_e32 v194, vcc, 0x6000, v194
	v_addc_co_u32_e32 v195, vcc, 0, v195, vcc
	ds_read_b128 v[98:101], v8 offset:4096
	ds_read_b128 v[102:105], v8 offset:8192
	ds_read_b128 v[106:109], v8 offset:12288
	ds_read_b128 v[110:113], v8 offset:16384
	ds_read_b128 v[114:117], v8 offset:20480
	ds_read_b128 v[118:121], v8 offset:24576
	ds_read_b128 v[122:125], v8 offset:28672
	ds_read_b128 v[126:129], v8
	ds_read_b128 v[134:137], v8 offset:32768
	v_add_u32_e32 v8, 16, v8
	s_waitcnt vmcnt(40) lgkmcnt(0)
	v_pk_fma_f32 v[196:197], v[166:167], v[126:127], v[196:197]
	v_pk_fma_f32 v[198:199], v[166:167], v[98:99], v[198:199]
	v_pk_fma_f32 v[200:201], v[166:167], v[102:103], v[200:201]
	v_pk_fma_f32 v[202:203], v[166:167], v[106:107], v[202:203]
	v_pk_fma_f32 v[204:205], v[166:167], v[110:111], v[204:205]
	v_pk_fma_f32 v[206:207], v[166:167], v[114:115], v[206:207]
	v_pk_fma_f32 v[208:209], v[166:167], v[118:119], v[208:209]
	v_pk_fma_f32 v[210:211], v[166:167], v[122:123], v[210:211]
	v_pk_fma_f32 v[212:213], v[166:167], v[134:135], v[212:213]
	v_pk_fma_f32 v[196:197], v[168:169], v[128:129], v[196:197]
	v_pk_fma_f32 v[198:199], v[168:169], v[100:101], v[198:199]
	v_pk_fma_f32 v[200:201], v[168:169], v[104:105], v[200:201]
	v_pk_fma_f32 v[202:203], v[168:169], v[108:109], v[202:203]
	v_pk_fma_f32 v[204:205], v[168:169], v[112:113], v[204:205]
	v_pk_fma_f32 v[206:207], v[168:169], v[116:117], v[206:207]
	v_pk_fma_f32 v[208:209], v[168:169], v[120:121], v[208:209]
	v_pk_fma_f32 v[210:211], v[168:169], v[124:125], v[210:211]
	v_pk_fma_f32 v[212:213], v[168:169], v[136:137], v[212:213]
	global_load_dword v166, v[194:195], off
	v_add_co_u32_e32 v194, vcc, 0x6000, v194
	v_addc_co_u32_e32 v195, vcc, 0, v195, vcc
	global_load_dword v167, v[194:195], off
	v_add_co_u32_e32 v194, vcc, 0x6000, v194
	v_addc_co_u32_e32 v195, vcc, 0, v195, vcc
	global_load_dword v168, v[194:195], off
	v_add_co_u32_e32 v194, vcc, 0x6000, v194
	v_addc_co_u32_e32 v195, vcc, 0, v195, vcc
	global_load_dword v169, v[194:195], off
	v_add_co_u32_e32 v194, vcc, 0x6000, v194
	v_addc_co_u32_e32 v195, vcc, 0, v195, vcc
	ds_read_b128 v[98:101], v8 offset:4096
	ds_read_b128 v[102:105], v8 offset:8192
	ds_read_b128 v[106:109], v8 offset:12288
	ds_read_b128 v[110:113], v8 offset:16384
	ds_read_b128 v[114:117], v8 offset:20480
	ds_read_b128 v[118:121], v8 offset:24576
	ds_read_b128 v[122:125], v8 offset:28672
	ds_read_b128 v[126:129], v8
	ds_read_b128 v[134:137], v8 offset:32768
	v_add_u32_e32 v8, 16, v8
	s_waitcnt vmcnt(40) lgkmcnt(0)
	v_pk_fma_f32 v[196:197], v[170:171], v[126:127], v[196:197]
	v_pk_fma_f32 v[198:199], v[170:171], v[98:99], v[198:199]
	v_pk_fma_f32 v[200:201], v[170:171], v[102:103], v[200:201]
	v_pk_fma_f32 v[202:203], v[170:171], v[106:107], v[202:203]
	v_pk_fma_f32 v[204:205], v[170:171], v[110:111], v[204:205]
	v_pk_fma_f32 v[206:207], v[170:171], v[114:115], v[206:207]
	v_pk_fma_f32 v[208:209], v[170:171], v[118:119], v[208:209]
	v_pk_fma_f32 v[210:211], v[170:171], v[122:123], v[210:211]
	v_pk_fma_f32 v[212:213], v[170:171], v[134:135], v[212:213]
	v_pk_fma_f32 v[196:197], v[172:173], v[128:129], v[196:197]
	v_pk_fma_f32 v[198:199], v[172:173], v[100:101], v[198:199]
	v_pk_fma_f32 v[200:201], v[172:173], v[104:105], v[200:201]
	v_pk_fma_f32 v[202:203], v[172:173], v[108:109], v[202:203]
	v_pk_fma_f32 v[204:205], v[172:173], v[112:113], v[204:205]
	v_pk_fma_f32 v[206:207], v[172:173], v[116:117], v[206:207]
	v_pk_fma_f32 v[208:209], v[172:173], v[120:121], v[208:209]
	v_pk_fma_f32 v[210:211], v[172:173], v[124:125], v[210:211]
	v_pk_fma_f32 v[212:213], v[172:173], v[136:137], v[212:213]
	global_load_dword v170, v[194:195], off
	v_add_co_u32_e32 v194, vcc, 0x6000, v194
	v_addc_co_u32_e32 v195, vcc, 0, v195, vcc
	global_load_dword v171, v[194:195], off
	v_add_co_u32_e32 v194, vcc, 0x6000, v194
	v_addc_co_u32_e32 v195, vcc, 0, v195, vcc
	global_load_dword v172, v[194:195], off
	v_add_co_u32_e32 v194, vcc, 0x6000, v194
	v_addc_co_u32_e32 v195, vcc, 0, v195, vcc
	global_load_dword v173, v[194:195], off
	v_add_co_u32_e32 v194, vcc, 0x6000, v194
	v_addc_co_u32_e32 v195, vcc, 0, v195, vcc
	ds_read_b128 v[98:101], v8 offset:4096
	ds_read_b128 v[102:105], v8 offset:8192
	ds_read_b128 v[106:109], v8 offset:12288
	ds_read_b128 v[110:113], v8 offset:16384
	ds_read_b128 v[114:117], v8 offset:20480
	ds_read_b128 v[118:121], v8 offset:24576
	ds_read_b128 v[122:125], v8 offset:28672
	ds_read_b128 v[126:129], v8
	ds_read_b128 v[134:137], v8 offset:32768
	v_add_u32_e32 v8, 16, v8
	s_waitcnt vmcnt(40) lgkmcnt(0)
	v_pk_fma_f32 v[196:197], v[174:175], v[126:127], v[196:197]
	v_pk_fma_f32 v[198:199], v[174:175], v[98:99], v[198:199]
	v_pk_fma_f32 v[200:201], v[174:175], v[102:103], v[200:201]
	v_pk_fma_f32 v[202:203], v[174:175], v[106:107], v[202:203]
	v_pk_fma_f32 v[204:205], v[174:175], v[110:111], v[204:205]
	v_pk_fma_f32 v[206:207], v[174:175], v[114:115], v[206:207]
	v_pk_fma_f32 v[208:209], v[174:175], v[118:119], v[208:209]
	v_pk_fma_f32 v[210:211], v[174:175], v[122:123], v[210:211]
	v_pk_fma_f32 v[212:213], v[174:175], v[134:135], v[212:213]
	v_pk_fma_f32 v[196:197], v[176:177], v[128:129], v[196:197]
	v_pk_fma_f32 v[198:199], v[176:177], v[100:101], v[198:199]
	v_pk_fma_f32 v[200:201], v[176:177], v[104:105], v[200:201]
	v_pk_fma_f32 v[202:203], v[176:177], v[108:109], v[202:203]
	v_pk_fma_f32 v[204:205], v[176:177], v[112:113], v[204:205]
	v_pk_fma_f32 v[206:207], v[176:177], v[116:117], v[206:207]
	v_pk_fma_f32 v[208:209], v[176:177], v[120:121], v[208:209]
	v_pk_fma_f32 v[210:211], v[176:177], v[124:125], v[210:211]
	v_pk_fma_f32 v[212:213], v[176:177], v[136:137], v[212:213]
	global_load_dword v174, v[194:195], off
	v_add_co_u32_e32 v194, vcc, 0x6000, v194
	v_addc_co_u32_e32 v195, vcc, 0, v195, vcc
	global_load_dword v175, v[194:195], off
	v_add_co_u32_e32 v194, vcc, 0x6000, v194
	v_addc_co_u32_e32 v195, vcc, 0, v195, vcc
	global_load_dword v176, v[194:195], off
	v_add_co_u32_e32 v194, vcc, 0x6000, v194
	v_addc_co_u32_e32 v195, vcc, 0, v195, vcc
	global_load_dword v177, v[194:195], off
	v_add_co_u32_e32 v194, vcc, 0x6000, v194
	v_addc_co_u32_e32 v195, vcc, 0, v195, vcc
	ds_read_b128 v[98:101], v8 offset:4096
	ds_read_b128 v[102:105], v8 offset:8192
	ds_read_b128 v[106:109], v8 offset:12288
	ds_read_b128 v[110:113], v8 offset:16384
	ds_read_b128 v[114:117], v8 offset:20480
	ds_read_b128 v[118:121], v8 offset:24576
	ds_read_b128 v[122:125], v8 offset:28672
	ds_read_b128 v[126:129], v8
	ds_read_b128 v[134:137], v8 offset:32768
	v_add_u32_e32 v8, 16, v8
	s_waitcnt vmcnt(40) lgkmcnt(0)
	v_pk_fma_f32 v[196:197], v[178:179], v[126:127], v[196:197]
	v_pk_fma_f32 v[198:199], v[178:179], v[98:99], v[198:199]
	v_pk_fma_f32 v[200:201], v[178:179], v[102:103], v[200:201]
	v_pk_fma_f32 v[202:203], v[178:179], v[106:107], v[202:203]
	v_pk_fma_f32 v[204:205], v[178:179], v[110:111], v[204:205]
	v_pk_fma_f32 v[206:207], v[178:179], v[114:115], v[206:207]
	v_pk_fma_f32 v[208:209], v[178:179], v[118:119], v[208:209]
	v_pk_fma_f32 v[210:211], v[178:179], v[122:123], v[210:211]
	v_pk_fma_f32 v[212:213], v[178:179], v[134:135], v[212:213]
	v_pk_fma_f32 v[196:197], v[180:181], v[128:129], v[196:197]
	v_pk_fma_f32 v[198:199], v[180:181], v[100:101], v[198:199]
	v_pk_fma_f32 v[200:201], v[180:181], v[104:105], v[200:201]
	v_pk_fma_f32 v[202:203], v[180:181], v[108:109], v[202:203]
	v_pk_fma_f32 v[204:205], v[180:181], v[112:113], v[204:205]
	v_pk_fma_f32 v[206:207], v[180:181], v[116:117], v[206:207]
	v_pk_fma_f32 v[208:209], v[180:181], v[120:121], v[208:209]
	v_pk_fma_f32 v[210:211], v[180:181], v[124:125], v[210:211]
	v_pk_fma_f32 v[212:213], v[180:181], v[136:137], v[212:213]
	global_load_dword v178, v[194:195], off
	v_add_co_u32_e32 v194, vcc, 0x6000, v194
	v_addc_co_u32_e32 v195, vcc, 0, v195, vcc
	global_load_dword v179, v[194:195], off
	v_add_co_u32_e32 v194, vcc, 0x6000, v194
	v_addc_co_u32_e32 v195, vcc, 0, v195, vcc
	global_load_dword v180, v[194:195], off
	v_add_co_u32_e32 v194, vcc, 0x6000, v194
	v_addc_co_u32_e32 v195, vcc, 0, v195, vcc
	global_load_dword v181, v[194:195], off
	v_add_co_u32_e32 v194, vcc, 0x6000, v194
	v_addc_co_u32_e32 v195, vcc, 0, v195, vcc
	ds_read_b128 v[98:101], v8 offset:4096
	ds_read_b128 v[102:105], v8 offset:8192
	ds_read_b128 v[106:109], v8 offset:12288
	ds_read_b128 v[110:113], v8 offset:16384
	ds_read_b128 v[114:117], v8 offset:20480
	ds_read_b128 v[118:121], v8 offset:24576
	ds_read_b128 v[122:125], v8 offset:28672
	ds_read_b128 v[126:129], v8
	ds_read_b128 v[134:137], v8 offset:32768
	v_add_u32_e32 v8, 16, v8
	s_waitcnt vmcnt(40) lgkmcnt(0)
	v_pk_fma_f32 v[196:197], v[182:183], v[126:127], v[196:197]
	v_pk_fma_f32 v[198:199], v[182:183], v[98:99], v[198:199]
	v_pk_fma_f32 v[200:201], v[182:183], v[102:103], v[200:201]
	v_pk_fma_f32 v[202:203], v[182:183], v[106:107], v[202:203]
	v_pk_fma_f32 v[204:205], v[182:183], v[110:111], v[204:205]
	v_pk_fma_f32 v[206:207], v[182:183], v[114:115], v[206:207]
	v_pk_fma_f32 v[208:209], v[182:183], v[118:119], v[208:209]
	v_pk_fma_f32 v[210:211], v[182:183], v[122:123], v[210:211]
	v_pk_fma_f32 v[212:213], v[182:183], v[134:135], v[212:213]
	v_pk_fma_f32 v[196:197], v[184:185], v[128:129], v[196:197]
	v_pk_fma_f32 v[198:199], v[184:185], v[100:101], v[198:199]
	v_pk_fma_f32 v[200:201], v[184:185], v[104:105], v[200:201]
	v_pk_fma_f32 v[202:203], v[184:185], v[108:109], v[202:203]
	v_pk_fma_f32 v[204:205], v[184:185], v[112:113], v[204:205]
	v_pk_fma_f32 v[206:207], v[184:185], v[116:117], v[206:207]
	v_pk_fma_f32 v[208:209], v[184:185], v[120:121], v[208:209]
	v_pk_fma_f32 v[210:211], v[184:185], v[124:125], v[210:211]
	v_pk_fma_f32 v[212:213], v[184:185], v[136:137], v[212:213]
	global_load_dword v182, v[194:195], off
	v_add_co_u32_e32 v194, vcc, 0x6000, v194
	v_addc_co_u32_e32 v195, vcc, 0, v195, vcc
	global_load_dword v183, v[194:195], off
	v_add_co_u32_e32 v194, vcc, 0x6000, v194
	v_addc_co_u32_e32 v195, vcc, 0, v195, vcc
	global_load_dword v184, v[194:195], off
	v_add_co_u32_e32 v194, vcc, 0x6000, v194
	v_addc_co_u32_e32 v195, vcc, 0, v195, vcc
	global_load_dword v185, v[194:195], off
	v_add_co_u32_e32 v194, vcc, 0x6000, v194
	v_addc_co_u32_e32 v195, vcc, 0, v195, vcc
	ds_read_b128 v[98:101], v8 offset:4096
	ds_read_b128 v[102:105], v8 offset:8192
	ds_read_b128 v[106:109], v8 offset:12288
	ds_read_b128 v[110:113], v8 offset:16384
	ds_read_b128 v[114:117], v8 offset:20480
	ds_read_b128 v[118:121], v8 offset:24576
	ds_read_b128 v[122:125], v8 offset:28672
	ds_read_b128 v[126:129], v8
	ds_read_b128 v[134:137], v8 offset:32768
	v_add_u32_e32 v8, 16, v8
	s_waitcnt vmcnt(40) lgkmcnt(0)
	v_pk_fma_f32 v[196:197], v[186:187], v[126:127], v[196:197]
	v_pk_fma_f32 v[198:199], v[186:187], v[98:99], v[198:199]
	v_pk_fma_f32 v[200:201], v[186:187], v[102:103], v[200:201]
	v_pk_fma_f32 v[202:203], v[186:187], v[106:107], v[202:203]
	v_pk_fma_f32 v[204:205], v[186:187], v[110:111], v[204:205]
	v_pk_fma_f32 v[206:207], v[186:187], v[114:115], v[206:207]
	v_pk_fma_f32 v[208:209], v[186:187], v[118:119], v[208:209]
	v_pk_fma_f32 v[210:211], v[186:187], v[122:123], v[210:211]
	v_pk_fma_f32 v[212:213], v[186:187], v[134:135], v[212:213]
	v_pk_fma_f32 v[196:197], v[188:189], v[128:129], v[196:197]
	v_pk_fma_f32 v[198:199], v[188:189], v[100:101], v[198:199]
	v_pk_fma_f32 v[200:201], v[188:189], v[104:105], v[200:201]
	v_pk_fma_f32 v[202:203], v[188:189], v[108:109], v[202:203]
	v_pk_fma_f32 v[204:205], v[188:189], v[112:113], v[204:205]
	v_pk_fma_f32 v[206:207], v[188:189], v[116:117], v[206:207]
	v_pk_fma_f32 v[208:209], v[188:189], v[120:121], v[208:209]
	v_pk_fma_f32 v[210:211], v[188:189], v[124:125], v[210:211]
	v_pk_fma_f32 v[212:213], v[188:189], v[136:137], v[212:213]
	global_load_dword v186, v[194:195], off
	v_add_co_u32_e32 v194, vcc, 0x6000, v194
	v_addc_co_u32_e32 v195, vcc, 0, v195, vcc
	global_load_dword v187, v[194:195], off
	v_add_co_u32_e32 v194, vcc, 0x6000, v194
	v_addc_co_u32_e32 v195, vcc, 0, v195, vcc
	global_load_dword v188, v[194:195], off
	v_add_co_u32_e32 v194, vcc, 0x6000, v194
	v_addc_co_u32_e32 v195, vcc, 0, v195, vcc
	global_load_dword v189, v[194:195], off
	ds_read_b128 v[98:101], v8 offset:4096
	ds_read_b128 v[102:105], v8 offset:8192
	ds_read_b128 v[106:109], v8 offset:12288
	ds_read_b128 v[110:113], v8 offset:16384
	ds_read_b128 v[114:117], v8 offset:20480
	ds_read_b128 v[118:121], v8 offset:24576
	ds_read_b128 v[122:125], v8 offset:28672
	ds_read_b128 v[126:129], v8
	ds_read_b128 v[134:137], v8 offset:32768
	v_add_u32_e32 v8, 16, v8
	s_waitcnt vmcnt(40) lgkmcnt(0)
	v_pk_fma_f32 v[196:197], v[190:191], v[126:127], v[196:197]
	v_pk_fma_f32 v[198:199], v[190:191], v[98:99], v[198:199]
	v_pk_fma_f32 v[200:201], v[190:191], v[102:103], v[200:201]
	v_pk_fma_f32 v[202:203], v[190:191], v[106:107], v[202:203]
	v_pk_fma_f32 v[204:205], v[190:191], v[110:111], v[204:205]
	v_pk_fma_f32 v[206:207], v[190:191], v[114:115], v[206:207]
	v_pk_fma_f32 v[208:209], v[190:191], v[118:119], v[208:209]
	v_pk_fma_f32 v[210:211], v[190:191], v[122:123], v[210:211]
	v_pk_fma_f32 v[212:213], v[190:191], v[134:135], v[212:213]
	v_pk_fma_f32 v[196:197], v[192:193], v[128:129], v[196:197]
	v_pk_fma_f32 v[198:199], v[192:193], v[100:101], v[198:199]
	v_pk_fma_f32 v[200:201], v[192:193], v[104:105], v[200:201]
	v_pk_fma_f32 v[202:203], v[192:193], v[108:109], v[202:203]
	v_pk_fma_f32 v[204:205], v[192:193], v[112:113], v[204:205]
	v_pk_fma_f32 v[206:207], v[192:193], v[116:117], v[206:207]
	v_pk_fma_f32 v[208:209], v[192:193], v[120:121], v[208:209]
	v_pk_fma_f32 v[210:211], v[192:193], v[124:125], v[210:211]
	v_pk_fma_f32 v[212:213], v[192:193], v[136:137], v[212:213]
	ds_read_b128 v[98:101], v8 offset:4096
	ds_read_b128 v[102:105], v8 offset:8192
	ds_read_b128 v[106:109], v8 offset:12288
	ds_read_b128 v[110:113], v8 offset:16384
	ds_read_b128 v[114:117], v8 offset:20480
	ds_read_b128 v[118:121], v8 offset:24576
	ds_read_b128 v[122:125], v8 offset:28672
	ds_read_b128 v[126:129], v8
	ds_read_b128 v[134:137], v8 offset:32768
	v_add_u32_e32 v8, 16, v8
	s_waitcnt vmcnt(36) lgkmcnt(0)
	v_pk_fma_f32 v[196:197], v[150:151], v[126:127], v[196:197]
	v_pk_fma_f32 v[198:199], v[150:151], v[98:99], v[198:199]
	v_pk_fma_f32 v[200:201], v[150:151], v[102:103], v[200:201]
	v_pk_fma_f32 v[202:203], v[150:151], v[106:107], v[202:203]
	v_pk_fma_f32 v[204:205], v[150:151], v[110:111], v[204:205]
	v_pk_fma_f32 v[206:207], v[150:151], v[114:115], v[206:207]
	v_pk_fma_f32 v[208:209], v[150:151], v[118:119], v[208:209]
	v_pk_fma_f32 v[210:211], v[150:151], v[122:123], v[210:211]
	v_pk_fma_f32 v[212:213], v[150:151], v[134:135], v[212:213]
	v_pk_fma_f32 v[196:197], v[152:153], v[128:129], v[196:197]
	v_pk_fma_f32 v[198:199], v[152:153], v[100:101], v[198:199]
	v_pk_fma_f32 v[200:201], v[152:153], v[104:105], v[200:201]
	v_pk_fma_f32 v[202:203], v[152:153], v[108:109], v[202:203]
	v_pk_fma_f32 v[204:205], v[152:153], v[112:113], v[204:205]
	v_pk_fma_f32 v[206:207], v[152:153], v[116:117], v[206:207]
	v_pk_fma_f32 v[208:209], v[152:153], v[120:121], v[208:209]
	v_pk_fma_f32 v[210:211], v[152:153], v[124:125], v[210:211]
	v_pk_fma_f32 v[212:213], v[152:153], v[136:137], v[212:213]
	ds_read_b128 v[98:101], v8 offset:4096
	ds_read_b128 v[102:105], v8 offset:8192
	ds_read_b128 v[106:109], v8 offset:12288
	ds_read_b128 v[110:113], v8 offset:16384
	ds_read_b128 v[114:117], v8 offset:20480
	ds_read_b128 v[118:121], v8 offset:24576
	ds_read_b128 v[122:125], v8 offset:28672
	ds_read_b128 v[126:129], v8
	ds_read_b128 v[134:137], v8 offset:32768
	v_add_u32_e32 v8, 16, v8
	s_waitcnt vmcnt(32) lgkmcnt(0)
	v_pk_fma_f32 v[196:197], v[154:155], v[126:127], v[196:197]
	v_pk_fma_f32 v[198:199], v[154:155], v[98:99], v[198:199]
	v_pk_fma_f32 v[200:201], v[154:155], v[102:103], v[200:201]
	v_pk_fma_f32 v[202:203], v[154:155], v[106:107], v[202:203]
	v_pk_fma_f32 v[204:205], v[154:155], v[110:111], v[204:205]
	v_pk_fma_f32 v[206:207], v[154:155], v[114:115], v[206:207]
	v_pk_fma_f32 v[208:209], v[154:155], v[118:119], v[208:209]
	v_pk_fma_f32 v[210:211], v[154:155], v[122:123], v[210:211]
	v_pk_fma_f32 v[212:213], v[154:155], v[134:135], v[212:213]
	v_pk_fma_f32 v[196:197], v[156:157], v[128:129], v[196:197]
	v_pk_fma_f32 v[198:199], v[156:157], v[100:101], v[198:199]
	v_pk_fma_f32 v[200:201], v[156:157], v[104:105], v[200:201]
	v_pk_fma_f32 v[202:203], v[156:157], v[108:109], v[202:203]
	v_pk_fma_f32 v[204:205], v[156:157], v[112:113], v[204:205]
	v_pk_fma_f32 v[206:207], v[156:157], v[116:117], v[206:207]
	v_pk_fma_f32 v[208:209], v[156:157], v[120:121], v[208:209]
	v_pk_fma_f32 v[210:211], v[156:157], v[124:125], v[210:211]
	v_pk_fma_f32 v[212:213], v[156:157], v[136:137], v[212:213]
	ds_read_b128 v[98:101], v8 offset:4096
	ds_read_b128 v[102:105], v8 offset:8192
	ds_read_b128 v[106:109], v8 offset:12288
	ds_read_b128 v[110:113], v8 offset:16384
	ds_read_b128 v[114:117], v8 offset:20480
	ds_read_b128 v[118:121], v8 offset:24576
	ds_read_b128 v[122:125], v8 offset:28672
	ds_read_b128 v[126:129], v8
	ds_read_b128 v[134:137], v8 offset:32768
	v_add_u32_e32 v8, 16, v8
	s_waitcnt vmcnt(28) lgkmcnt(0)
	v_pk_fma_f32 v[196:197], v[158:159], v[126:127], v[196:197]
	v_pk_fma_f32 v[198:199], v[158:159], v[98:99], v[198:199]
	v_pk_fma_f32 v[200:201], v[158:159], v[102:103], v[200:201]
	v_pk_fma_f32 v[202:203], v[158:159], v[106:107], v[202:203]
	v_pk_fma_f32 v[204:205], v[158:159], v[110:111], v[204:205]
	v_pk_fma_f32 v[206:207], v[158:159], v[114:115], v[206:207]
	v_pk_fma_f32 v[208:209], v[158:159], v[118:119], v[208:209]
	v_pk_fma_f32 v[210:211], v[158:159], v[122:123], v[210:211]
	v_pk_fma_f32 v[212:213], v[158:159], v[134:135], v[212:213]
	v_pk_fma_f32 v[196:197], v[160:161], v[128:129], v[196:197]
	v_pk_fma_f32 v[198:199], v[160:161], v[100:101], v[198:199]
	v_pk_fma_f32 v[200:201], v[160:161], v[104:105], v[200:201]
	v_pk_fma_f32 v[202:203], v[160:161], v[108:109], v[202:203]
	v_pk_fma_f32 v[204:205], v[160:161], v[112:113], v[204:205]
	v_pk_fma_f32 v[206:207], v[160:161], v[116:117], v[206:207]
	v_pk_fma_f32 v[208:209], v[160:161], v[120:121], v[208:209]
	v_pk_fma_f32 v[210:211], v[160:161], v[124:125], v[210:211]
	v_pk_fma_f32 v[212:213], v[160:161], v[136:137], v[212:213]
	ds_read_b128 v[98:101], v8 offset:4096
	ds_read_b128 v[102:105], v8 offset:8192
	ds_read_b128 v[106:109], v8 offset:12288
	ds_read_b128 v[110:113], v8 offset:16384
	ds_read_b128 v[114:117], v8 offset:20480
	ds_read_b128 v[118:121], v8 offset:24576
	ds_read_b128 v[122:125], v8 offset:28672
	ds_read_b128 v[126:129], v8
	ds_read_b128 v[134:137], v8 offset:32768
	v_add_u32_e32 v8, 16, v8
	s_waitcnt vmcnt(24) lgkmcnt(0)
	v_pk_fma_f32 v[196:197], v[162:163], v[126:127], v[196:197]
	v_pk_fma_f32 v[198:199], v[162:163], v[98:99], v[198:199]
	v_pk_fma_f32 v[200:201], v[162:163], v[102:103], v[200:201]
	v_pk_fma_f32 v[202:203], v[162:163], v[106:107], v[202:203]
	v_pk_fma_f32 v[204:205], v[162:163], v[110:111], v[204:205]
	v_pk_fma_f32 v[206:207], v[162:163], v[114:115], v[206:207]
	v_pk_fma_f32 v[208:209], v[162:163], v[118:119], v[208:209]
	v_pk_fma_f32 v[210:211], v[162:163], v[122:123], v[210:211]
	v_pk_fma_f32 v[212:213], v[162:163], v[134:135], v[212:213]
	v_pk_fma_f32 v[196:197], v[164:165], v[128:129], v[196:197]
	v_pk_fma_f32 v[198:199], v[164:165], v[100:101], v[198:199]
	v_pk_fma_f32 v[200:201], v[164:165], v[104:105], v[200:201]
	v_pk_fma_f32 v[202:203], v[164:165], v[108:109], v[202:203]
	v_pk_fma_f32 v[204:205], v[164:165], v[112:113], v[204:205]
	v_pk_fma_f32 v[206:207], v[164:165], v[116:117], v[206:207]
	v_pk_fma_f32 v[208:209], v[164:165], v[120:121], v[208:209]
	v_pk_fma_f32 v[210:211], v[164:165], v[124:125], v[210:211]
	v_pk_fma_f32 v[212:213], v[164:165], v[136:137], v[212:213]
	ds_read_b128 v[98:101], v8 offset:4096
	ds_read_b128 v[102:105], v8 offset:8192
	ds_read_b128 v[106:109], v8 offset:12288
	ds_read_b128 v[110:113], v8 offset:16384
	ds_read_b128 v[114:117], v8 offset:20480
	ds_read_b128 v[118:121], v8 offset:24576
	ds_read_b128 v[122:125], v8 offset:28672
	ds_read_b128 v[126:129], v8
	ds_read_b128 v[134:137], v8 offset:32768
	v_add_u32_e32 v8, 16, v8
	s_waitcnt vmcnt(20) lgkmcnt(0)
	v_pk_fma_f32 v[196:197], v[166:167], v[126:127], v[196:197]
	v_pk_fma_f32 v[198:199], v[166:167], v[98:99], v[198:199]
	v_pk_fma_f32 v[200:201], v[166:167], v[102:103], v[200:201]
	v_pk_fma_f32 v[202:203], v[166:167], v[106:107], v[202:203]
	v_pk_fma_f32 v[204:205], v[166:167], v[110:111], v[204:205]
	v_pk_fma_f32 v[206:207], v[166:167], v[114:115], v[206:207]
	v_pk_fma_f32 v[208:209], v[166:167], v[118:119], v[208:209]
	v_pk_fma_f32 v[210:211], v[166:167], v[122:123], v[210:211]
	v_pk_fma_f32 v[212:213], v[166:167], v[134:135], v[212:213]
	v_pk_fma_f32 v[196:197], v[168:169], v[128:129], v[196:197]
	v_pk_fma_f32 v[198:199], v[168:169], v[100:101], v[198:199]
	v_pk_fma_f32 v[200:201], v[168:169], v[104:105], v[200:201]
	v_pk_fma_f32 v[202:203], v[168:169], v[108:109], v[202:203]
	v_pk_fma_f32 v[204:205], v[168:169], v[112:113], v[204:205]
	v_pk_fma_f32 v[206:207], v[168:169], v[116:117], v[206:207]
	v_pk_fma_f32 v[208:209], v[168:169], v[120:121], v[208:209]
	v_pk_fma_f32 v[210:211], v[168:169], v[124:125], v[210:211]
	v_pk_fma_f32 v[212:213], v[168:169], v[136:137], v[212:213]
	ds_read_b128 v[98:101], v8 offset:4096
	ds_read_b128 v[102:105], v8 offset:8192
	ds_read_b128 v[106:109], v8 offset:12288
	ds_read_b128 v[110:113], v8 offset:16384
	ds_read_b128 v[114:117], v8 offset:20480
	ds_read_b128 v[118:121], v8 offset:24576
	ds_read_b128 v[122:125], v8 offset:28672
	ds_read_b128 v[126:129], v8
	ds_read_b128 v[134:137], v8 offset:32768
	v_add_u32_e32 v8, 16, v8
	s_waitcnt vmcnt(16) lgkmcnt(0)
	v_pk_fma_f32 v[196:197], v[170:171], v[126:127], v[196:197]
	v_pk_fma_f32 v[198:199], v[170:171], v[98:99], v[198:199]
	v_pk_fma_f32 v[200:201], v[170:171], v[102:103], v[200:201]
	v_pk_fma_f32 v[202:203], v[170:171], v[106:107], v[202:203]
	v_pk_fma_f32 v[204:205], v[170:171], v[110:111], v[204:205]
	v_pk_fma_f32 v[206:207], v[170:171], v[114:115], v[206:207]
	v_pk_fma_f32 v[208:209], v[170:171], v[118:119], v[208:209]
	v_pk_fma_f32 v[210:211], v[170:171], v[122:123], v[210:211]
	v_pk_fma_f32 v[212:213], v[170:171], v[134:135], v[212:213]
	v_pk_fma_f32 v[196:197], v[172:173], v[128:129], v[196:197]
	v_pk_fma_f32 v[198:199], v[172:173], v[100:101], v[198:199]
	v_pk_fma_f32 v[200:201], v[172:173], v[104:105], v[200:201]
	v_pk_fma_f32 v[202:203], v[172:173], v[108:109], v[202:203]
	v_pk_fma_f32 v[204:205], v[172:173], v[112:113], v[204:205]
	v_pk_fma_f32 v[206:207], v[172:173], v[116:117], v[206:207]
	v_pk_fma_f32 v[208:209], v[172:173], v[120:121], v[208:209]
	v_pk_fma_f32 v[210:211], v[172:173], v[124:125], v[210:211]
	v_pk_fma_f32 v[212:213], v[172:173], v[136:137], v[212:213]
	ds_read_b128 v[98:101], v8 offset:4096
	ds_read_b128 v[102:105], v8 offset:8192
	ds_read_b128 v[106:109], v8 offset:12288
	ds_read_b128 v[110:113], v8 offset:16384
	ds_read_b128 v[114:117], v8 offset:20480
	ds_read_b128 v[118:121], v8 offset:24576
	ds_read_b128 v[122:125], v8 offset:28672
	ds_read_b128 v[126:129], v8
	ds_read_b128 v[134:137], v8 offset:32768
	v_add_u32_e32 v8, 16, v8
	s_waitcnt vmcnt(12) lgkmcnt(0)
	v_pk_fma_f32 v[196:197], v[174:175], v[126:127], v[196:197]
	v_pk_fma_f32 v[198:199], v[174:175], v[98:99], v[198:199]
	v_pk_fma_f32 v[200:201], v[174:175], v[102:103], v[200:201]
	v_pk_fma_f32 v[202:203], v[174:175], v[106:107], v[202:203]
	v_pk_fma_f32 v[204:205], v[174:175], v[110:111], v[204:205]
	v_pk_fma_f32 v[206:207], v[174:175], v[114:115], v[206:207]
	v_pk_fma_f32 v[208:209], v[174:175], v[118:119], v[208:209]
	v_pk_fma_f32 v[210:211], v[174:175], v[122:123], v[210:211]
	v_pk_fma_f32 v[212:213], v[174:175], v[134:135], v[212:213]
	v_pk_fma_f32 v[196:197], v[176:177], v[128:129], v[196:197]
	v_pk_fma_f32 v[198:199], v[176:177], v[100:101], v[198:199]
	v_pk_fma_f32 v[200:201], v[176:177], v[104:105], v[200:201]
	v_pk_fma_f32 v[202:203], v[176:177], v[108:109], v[202:203]
	v_pk_fma_f32 v[204:205], v[176:177], v[112:113], v[204:205]
	v_pk_fma_f32 v[206:207], v[176:177], v[116:117], v[206:207]
	v_pk_fma_f32 v[208:209], v[176:177], v[120:121], v[208:209]
	v_pk_fma_f32 v[210:211], v[176:177], v[124:125], v[210:211]
	v_pk_fma_f32 v[212:213], v[176:177], v[136:137], v[212:213]
	ds_read_b128 v[98:101], v8 offset:4096
	ds_read_b128 v[102:105], v8 offset:8192
	ds_read_b128 v[106:109], v8 offset:12288
	ds_read_b128 v[110:113], v8 offset:16384
	ds_read_b128 v[114:117], v8 offset:20480
	ds_read_b128 v[118:121], v8 offset:24576
	ds_read_b128 v[122:125], v8 offset:28672
	ds_read_b128 v[126:129], v8
	ds_read_b128 v[134:137], v8 offset:32768
	v_add_u32_e32 v8, 16, v8
	s_waitcnt vmcnt(8) lgkmcnt(0)
	v_pk_fma_f32 v[196:197], v[178:179], v[126:127], v[196:197]
	v_pk_fma_f32 v[198:199], v[178:179], v[98:99], v[198:199]
	v_pk_fma_f32 v[200:201], v[178:179], v[102:103], v[200:201]
	v_pk_fma_f32 v[202:203], v[178:179], v[106:107], v[202:203]
	v_pk_fma_f32 v[204:205], v[178:179], v[110:111], v[204:205]
	v_pk_fma_f32 v[206:207], v[178:179], v[114:115], v[206:207]
	v_pk_fma_f32 v[208:209], v[178:179], v[118:119], v[208:209]
	v_pk_fma_f32 v[210:211], v[178:179], v[122:123], v[210:211]
	v_pk_fma_f32 v[212:213], v[178:179], v[134:135], v[212:213]
	v_pk_fma_f32 v[196:197], v[180:181], v[128:129], v[196:197]
	v_pk_fma_f32 v[198:199], v[180:181], v[100:101], v[198:199]
	v_pk_fma_f32 v[200:201], v[180:181], v[104:105], v[200:201]
	v_pk_fma_f32 v[202:203], v[180:181], v[108:109], v[202:203]
	v_pk_fma_f32 v[204:205], v[180:181], v[112:113], v[204:205]
	v_pk_fma_f32 v[206:207], v[180:181], v[116:117], v[206:207]
	v_pk_fma_f32 v[208:209], v[180:181], v[120:121], v[208:209]
	v_pk_fma_f32 v[210:211], v[180:181], v[124:125], v[210:211]
	v_pk_fma_f32 v[212:213], v[180:181], v[136:137], v[212:213]
	ds_read_b128 v[98:101], v8 offset:4096
	ds_read_b128 v[102:105], v8 offset:8192
	ds_read_b128 v[106:109], v8 offset:12288
	ds_read_b128 v[110:113], v8 offset:16384
	ds_read_b128 v[114:117], v8 offset:20480
	ds_read_b128 v[118:121], v8 offset:24576
	ds_read_b128 v[122:125], v8 offset:28672
	ds_read_b128 v[126:129], v8
	ds_read_b128 v[134:137], v8 offset:32768
	v_add_u32_e32 v8, 16, v8
	s_waitcnt vmcnt(4) lgkmcnt(0)
	v_pk_fma_f32 v[196:197], v[182:183], v[126:127], v[196:197]
	v_pk_fma_f32 v[198:199], v[182:183], v[98:99], v[198:199]
	v_pk_fma_f32 v[200:201], v[182:183], v[102:103], v[200:201]
	v_pk_fma_f32 v[202:203], v[182:183], v[106:107], v[202:203]
	v_pk_fma_f32 v[204:205], v[182:183], v[110:111], v[204:205]
	v_pk_fma_f32 v[206:207], v[182:183], v[114:115], v[206:207]
	v_pk_fma_f32 v[208:209], v[182:183], v[118:119], v[208:209]
	v_pk_fma_f32 v[210:211], v[182:183], v[122:123], v[210:211]
	v_pk_fma_f32 v[212:213], v[182:183], v[134:135], v[212:213]
	v_pk_fma_f32 v[196:197], v[184:185], v[128:129], v[196:197]
	v_pk_fma_f32 v[198:199], v[184:185], v[100:101], v[198:199]
	v_pk_fma_f32 v[200:201], v[184:185], v[104:105], v[200:201]
	v_pk_fma_f32 v[202:203], v[184:185], v[108:109], v[202:203]
	v_pk_fma_f32 v[204:205], v[184:185], v[112:113], v[204:205]
	v_pk_fma_f32 v[206:207], v[184:185], v[116:117], v[206:207]
	v_pk_fma_f32 v[208:209], v[184:185], v[120:121], v[208:209]
	v_pk_fma_f32 v[210:211], v[184:185], v[124:125], v[210:211]
	v_pk_fma_f32 v[212:213], v[184:185], v[136:137], v[212:213]
	ds_read_b128 v[98:101], v8 offset:4096
	ds_read_b128 v[102:105], v8 offset:8192
	ds_read_b128 v[106:109], v8 offset:12288
	ds_read_b128 v[110:113], v8 offset:16384
	ds_read_b128 v[114:117], v8 offset:20480
	ds_read_b128 v[118:121], v8 offset:24576
	ds_read_b128 v[122:125], v8 offset:28672
	ds_read_b128 v[126:129], v8
	ds_read_b128 v[134:137], v8 offset:32768
	v_add_u32_e32 v8, 16, v8
	s_waitcnt vmcnt(0) lgkmcnt(0)
	v_pk_fma_f32 v[196:197], v[186:187], v[126:127], v[196:197]
	v_pk_fma_f32 v[198:199], v[186:187], v[98:99], v[198:199]
	v_pk_fma_f32 v[200:201], v[186:187], v[102:103], v[200:201]
	v_pk_fma_f32 v[202:203], v[186:187], v[106:107], v[202:203]
	v_pk_fma_f32 v[204:205], v[186:187], v[110:111], v[204:205]
	v_pk_fma_f32 v[206:207], v[186:187], v[114:115], v[206:207]
	v_pk_fma_f32 v[208:209], v[186:187], v[118:119], v[208:209]
	v_pk_fma_f32 v[210:211], v[186:187], v[122:123], v[210:211]
	v_pk_fma_f32 v[212:213], v[186:187], v[134:135], v[212:213]
	v_pk_fma_f32 v[196:197], v[188:189], v[128:129], v[196:197]
	v_pk_fma_f32 v[198:199], v[188:189], v[100:101], v[198:199]
	v_pk_fma_f32 v[200:201], v[188:189], v[104:105], v[200:201]
	v_pk_fma_f32 v[202:203], v[188:189], v[108:109], v[202:203]
	v_pk_fma_f32 v[204:205], v[188:189], v[112:113], v[204:205]
	v_pk_fma_f32 v[206:207], v[188:189], v[116:117], v[206:207]
	v_pk_fma_f32 v[208:209], v[188:189], v[120:121], v[208:209]
	v_pk_fma_f32 v[210:211], v[188:189], v[124:125], v[210:211]
	v_pk_fma_f32 v[212:213], v[188:189], v[136:137], v[212:213]
	v_add_f32_e32 v4, v196, v197
	v_add_f32_e32 v5, v198, v199
	v_add_f32_e32 v68, v200, v201
	v_add_f32_e32 v69, v202, v203
	v_add_f32_e32 v70, v204, v205
	v_add_f32_e32 v71, v206, v207
	v_add_f32_e32 v72, v208, v209
	v_add_f32_e32 v73, v210, v211
	v_add_f32_e32 v23, v212, v213
	v_add_u32_e32 v2, 0x9000, v76
	ds_write2_b32 v2, v4, v5 offset1:32
	ds_write2_b32 v2, v68, v69 offset0:64 offset1:96
	ds_write2_b32 v2, v70, v71 offset0:128 offset1:160
	ds_write2_b32 v2, v72, v73 offset0:192 offset1:224
	ds_write_b32 v76, v23 offset:37888
	v_mov_b32_e32 v2, s63
	v_mov_b32_e32 v4, s75
	s_waitcnt lgkmcnt(0)
	s_barrier
	ds_read_b64 v[2:3], v2
	ds_read_b64 v[4:5], v4
	v_lshl_or_b32 v8, v1, 5, v74
	v_add_u32_e32 v8, 0xfffdd800, v8
	s_mov_b64 s[52:53], 0
	s_waitcnt lgkmcnt(1)
	v_lshl_add_u64 v[2:3], v[2:3], 0, s[36:37]
	s_waitcnt lgkmcnt(0)
	v_lshl_add_u64 v[4:5], v[8:9], 2, v[4:5]
	v_mov_b32_e32 v8, v84
	v_mov_b32_e32 v23, v83
	v_mov_b32_e32 v61, v82
	v_mov_b32_e32 v65, v89
